# combined: saddr-form LDS-DMA addressing in five GEMM K-loops (no 64-bit VALU adds), permlane-swap reductions in attention, P4 epilogue rstd broadcasts via op_sel_hi, interleaved SGU LayerNorm reductio
# speedup vs baseline: 1.0067x; 1.0067x over previous
.LBB0_245:
	ds_read_b128 v[144:147], v178
	ds_read_b128 v[148:151], v178 offset:1024
	ds_read_b128 v[152:155], v178 offset:2048
	ds_read_b128 v[156:159], v178 offset:3072
	ds_read_b128 v[160:163], v179
	ds_read_b128 v[164:167], v179 offset:1024
	ds_read_b128 v[168:171], v179 offset:2048
	ds_read_b128 v[182:185], v179 offset:3072
	s_add_u32 s46, s44, 0xfffc0080
	s_addc_u32 s47, s45, -1
	s_cmp_eq_u32 s63, 12
	s_cselect_b32 s49, s7, s47
	s_cselect_b32 s48, s37, s46
	s_cselect_b32 s47, s25, s62
	s_cselect_b32 s46, s43, s61
	s_add_i32 m0, s31, 0xc000
	ds_read_b128 v[186:189], v180
	ds_read_b128 v[190:193], v180 offset:1024
	ds_read_b128 v[194:197], v180 offset:2048
	ds_read_b128 v[198:201], v180 offset:3072
	ds_read_b128 v[202:205], v180 offset:4096
	ds_read_b128 v[210:213], v180 offset:5120
	ds_read_b128 v[214:217], v180 offset:6144
	ds_read_b128 v[218:221], v180 offset:7168
	global_load_lds_dwordx4 v136, s[44:45]
	s_add_i32 m0, s31, 0xe000
	s_nop 0
	global_load_lds_dwordx4 v138, s[44:45]
	s_waitcnt vmcnt(8)
	s_waitcnt lgkmcnt(0)
	s_barrier
	s_setprio 1
	s_waitcnt lgkmcnt(0)
	v_mfma_f32_16x16x32_bf16 v[124:127], v[144:147], v[186:189], v[124:127]
	v_mfma_f32_16x16x32_bf16 v[120:123], v[152:155], v[186:189], v[120:123]
	v_mfma_f32_16x16x32_bf16 v[108:111], v[144:147], v[194:197], v[108:111]
	v_mfma_f32_16x16x32_bf16 v[104:107], v[152:155], v[194:197], v[104:107]
	v_mfma_f32_16x16x32_bf16 v[92:95], v[144:147], v[202:205], v[92:95]
	v_mfma_f32_16x16x32_bf16 v[88:91], v[152:155], v[202:205], v[88:91]
	v_mfma_f32_16x16x32_bf16 v[76:79], v[144:147], v[214:217], v[76:79]
	v_mfma_f32_16x16x32_bf16 v[72:75], v[152:155], v[214:217], v[72:75]
	v_mfma_f32_16x16x32_bf16 v[124:127], v[148:151], v[190:193], v[124:127]
	v_mfma_f32_16x16x32_bf16 v[120:123], v[156:159], v[190:193], v[120:123]
	v_mfma_f32_16x16x32_bf16 v[108:111], v[148:151], v[198:201], v[108:111]
	v_mfma_f32_16x16x32_bf16 v[104:107], v[156:159], v[198:201], v[104:107]
	v_mfma_f32_16x16x32_bf16 v[92:95], v[148:151], v[210:213], v[92:95]
	v_mfma_f32_16x16x32_bf16 v[88:91], v[156:159], v[210:213], v[88:91]
	v_mfma_f32_16x16x32_bf16 v[76:79], v[148:151], v[218:221], v[76:79]
	v_mfma_f32_16x16x32_bf16 v[72:75], v[156:159], v[218:221], v[72:75]
	v_mfma_f32_16x16x32_bf16 v[116:119], v[160:163], v[186:189], v[116:119]
	v_mfma_f32_16x16x32_bf16 v[112:115], v[168:171], v[186:189], v[112:115]
	v_mfma_f32_16x16x32_bf16 v[100:103], v[160:163], v[194:197], v[100:103]
	v_mfma_f32_16x16x32_bf16 v[96:99], v[168:171], v[194:197], v[96:99]
	v_mfma_f32_16x16x32_bf16 v[84:87], v[160:163], v[202:205], v[84:87]
	v_mfma_f32_16x16x32_bf16 v[80:83], v[168:171], v[202:205], v[80:83]
	v_mfma_f32_16x16x32_bf16 v[68:71], v[160:163], v[214:217], v[68:71]
	v_mfma_f32_16x16x32_bf16 v[64:67], v[168:171], v[214:217], v[64:67]
	v_mfma_f32_16x16x32_bf16 v[116:119], v[164:167], v[190:193], v[116:119]
	v_mfma_f32_16x16x32_bf16 v[112:115], v[182:185], v[190:193], v[112:115]
	v_mfma_f32_16x16x32_bf16 v[100:103], v[164:167], v[198:201], v[100:103]
	v_mfma_f32_16x16x32_bf16 v[96:99], v[182:185], v[198:201], v[96:99]
	v_mfma_f32_16x16x32_bf16 v[84:87], v[164:167], v[210:213], v[84:87]
	v_mfma_f32_16x16x32_bf16 v[80:83], v[182:185], v[210:213], v[80:83]
	v_mfma_f32_16x16x32_bf16 v[68:71], v[164:167], v[218:221], v[68:71]
	v_mfma_f32_16x16x32_bf16 v[64:67], v[182:185], v[218:221], v[64:67]
	s_setprio 0
	s_barrier
	s_add_u32 s98, s46, s16
	s_addc_u32 s99, s47, s17
	s_add_u32 s100, s48, s16
	s_addc_u32 s101, s49, s17
	s_add_i32 s64, s35, s23
	s_mov_b32 m0, s64
	ds_read_b128 v[186:189], v180 offset:16384
	ds_read_b128 v[190:193], v180 offset:17408
	ds_read_b128 v[194:197], v180 offset:18432
	ds_read_b128 v[198:201], v180 offset:19456
	ds_read_b128 v[202:205], v180 offset:20480
	ds_read_b128 v[210:213], v180 offset:21504
	ds_read_b128 v[214:217], v180 offset:22528
	ds_read_b128 v[218:221], v180 offset:23552
	global_load_lds_dwordx4 v130, s[46:47]
	s_add_i32 m0, s64, 0x2000
	s_add_u32 s64, s46, 0x40000
	s_addc_u32 s65, s47, 0
	s_add_i32 s66, s59, s23
	global_load_lds_dwordx4 v134, s[46:47]
	s_mov_b32 m0, s66
	s_nop 0
	global_load_lds_dwordx4 v130, s[64:65]
	s_add_i32 m0, s66, 0x2000
	s_nop 0
	global_load_lds_dwordx4 v134, s[64:65]
	s_mov_b32 m0, s31
	s_nop 0
	global_load_lds_dwordx4 v128, s[48:49]
	s_mov_b32 m0, s50
	s_nop 0
	global_load_lds_dwordx4 v132, s[48:49]
	s_waitcnt vmcnt(8)
	s_waitcnt lgkmcnt(0)
	s_barrier
	s_setprio 1
	s_waitcnt lgkmcnt(0)
	v_mfma_f32_16x16x32_bf16 v[60:63], v[144:147], v[186:189], v[60:63]
	v_mfma_f32_16x16x32_bf16 v[56:59], v[152:155], v[186:189], v[56:59]
	v_mfma_f32_16x16x32_bf16 v[44:47], v[144:147], v[194:197], v[44:47]
	v_mfma_f32_16x16x32_bf16 v[40:43], v[152:155], v[194:197], v[40:43]
	v_mfma_f32_16x16x32_bf16 v[28:31], v[144:147], v[202:205], v[28:31]
	v_mfma_f32_16x16x32_bf16 v[24:27], v[152:155], v[202:205], v[24:27]
	v_mfma_f32_16x16x32_bf16 v[12:15], v[144:147], v[214:217], v[12:15]
	v_mfma_f32_16x16x32_bf16 v[8:11], v[152:155], v[214:217], v[8:11]
	v_mfma_f32_16x16x32_bf16 v[60:63], v[148:151], v[190:193], v[60:63]
	v_mfma_f32_16x16x32_bf16 v[56:59], v[156:159], v[190:193], v[56:59]
	v_mfma_f32_16x16x32_bf16 v[44:47], v[148:151], v[198:201], v[44:47]
	v_mfma_f32_16x16x32_bf16 v[40:43], v[156:159], v[198:201], v[40:43]
	v_mfma_f32_16x16x32_bf16 v[28:31], v[148:151], v[210:213], v[28:31]
	v_mfma_f32_16x16x32_bf16 v[24:27], v[156:159], v[210:213], v[24:27]
	v_mfma_f32_16x16x32_bf16 v[12:15], v[148:151], v[218:221], v[12:15]
	v_mfma_f32_16x16x32_bf16 v[8:11], v[156:159], v[218:221], v[8:11]
	v_mfma_f32_16x16x32_bf16 v[52:55], v[160:163], v[186:189], v[52:55]
	v_mfma_f32_16x16x32_bf16 v[48:51], v[168:171], v[186:189], v[48:51]
	v_mfma_f32_16x16x32_bf16 v[36:39], v[160:163], v[194:197], v[36:39]
	v_mfma_f32_16x16x32_bf16 v[32:35], v[168:171], v[194:197], v[32:35]
	v_mfma_f32_16x16x32_bf16 v[20:23], v[160:163], v[202:205], v[20:23]
	v_mfma_f32_16x16x32_bf16 v[16:19], v[168:171], v[202:205], v[16:19]
	v_mfma_f32_16x16x32_bf16 v[4:7], v[160:163], v[214:217], v[4:7]
	v_mfma_f32_16x16x32_bf16 v[0:3], v[168:171], v[214:217], v[0:3]
	v_mfma_f32_16x16x32_bf16 v[52:55], v[164:167], v[190:193], v[52:55]
	v_mfma_f32_16x16x32_bf16 v[48:51], v[182:185], v[190:193], v[48:51]
	v_mfma_f32_16x16x32_bf16 v[36:39], v[164:167], v[198:201], v[36:39]
	v_mfma_f32_16x16x32_bf16 v[32:35], v[182:185], v[198:201], v[32:35]
	v_mfma_f32_16x16x32_bf16 v[20:23], v[164:167], v[210:213], v[20:23]
	v_mfma_f32_16x16x32_bf16 v[16:19], v[182:185], v[210:213], v[16:19]
	v_mfma_f32_16x16x32_bf16 v[4:7], v[164:167], v[218:221], v[4:7]
	v_mfma_f32_16x16x32_bf16 v[0:3], v[182:185], v[218:221], v[0:3]
	s_setprio 0
	s_barrier
	s_add_i32 s64, 0, 0x18000
	s_add_i32 s65, 0, 0x1c000
	v_add_u32_e32 v156, s64, v176
	v_add_u32_e32 v181, s65, v176
	ds_read_b128 v[144:147], v156
	ds_read_b128 v[148:151], v156 offset:1024
	ds_read_b128 v[152:155], v156 offset:2048
	ds_read_b128 v[156:159], v156 offset:3072
	ds_read_b128 v[160:163], v181
	ds_read_b128 v[164:167], v181 offset:1024
	ds_read_b128 v[168:171], v181 offset:2048
	ds_read_b128 v[182:185], v181 offset:3072
	s_add_u32 s48, s48, 0x40000
	s_addc_u32 s49, s49, 0
	s_mov_b32 m0, s51
	ds_read_b128 v[186:189], v180 offset:32768
	ds_read_b128 v[190:193], v180 offset:33792
	ds_read_b128 v[194:197], v180 offset:34816
	ds_read_b128 v[198:201], v180 offset:35840
	ds_read_b128 v[202:205], v180 offset:36864
	ds_read_b128 v[210:213], v180 offset:37888
	ds_read_b128 v[214:217], v180 offset:38912
	ds_read_b128 v[218:221], v180 offset:39936
	global_load_lds_dwordx4 v128, s[48:49]
	s_mov_b32 m0, s52
	s_nop 0
	global_load_lds_dwordx4 v132, s[48:49]
	s_waitcnt vmcnt(8)
	s_waitcnt lgkmcnt(0)
	s_barrier
	s_setprio 1
	s_waitcnt lgkmcnt(0)
	v_mfma_f32_16x16x32_bf16 v[124:127], v[144:147], v[186:189], v[124:127]
	v_mfma_f32_16x16x32_bf16 v[120:123], v[152:155], v[186:189], v[120:123]
	v_mfma_f32_16x16x32_bf16 v[108:111], v[144:147], v[194:197], v[108:111]
	v_mfma_f32_16x16x32_bf16 v[104:107], v[152:155], v[194:197], v[104:107]
	v_mfma_f32_16x16x32_bf16 v[92:95], v[144:147], v[202:205], v[92:95]
	v_mfma_f32_16x16x32_bf16 v[88:91], v[152:155], v[202:205], v[88:91]
	v_mfma_f32_16x16x32_bf16 v[76:79], v[144:147], v[214:217], v[76:79]
	v_mfma_f32_16x16x32_bf16 v[72:75], v[152:155], v[214:217], v[72:75]
	v_mfma_f32_16x16x32_bf16 v[124:127], v[148:151], v[190:193], v[124:127]
	v_mfma_f32_16x16x32_bf16 v[120:123], v[156:159], v[190:193], v[120:123]
	v_mfma_f32_16x16x32_bf16 v[108:111], v[148:151], v[198:201], v[108:111]
	v_mfma_f32_16x16x32_bf16 v[104:107], v[156:159], v[198:201], v[104:107]
	v_mfma_f32_16x16x32_bf16 v[92:95], v[148:151], v[210:213], v[92:95]
	v_mfma_f32_16x16x32_bf16 v[88:91], v[156:159], v[210:213], v[88:91]
	v_mfma_f32_16x16x32_bf16 v[76:79], v[148:151], v[218:221], v[76:79]
	v_mfma_f32_16x16x32_bf16 v[72:75], v[156:159], v[218:221], v[72:75]
	v_mfma_f32_16x16x32_bf16 v[116:119], v[160:163], v[186:189], v[116:119]
	v_mfma_f32_16x16x32_bf16 v[112:115], v[168:171], v[186:189], v[112:115]
	v_mfma_f32_16x16x32_bf16 v[100:103], v[160:163], v[194:197], v[100:103]
	v_mfma_f32_16x16x32_bf16 v[96:99], v[168:171], v[194:197], v[96:99]
	v_mfma_f32_16x16x32_bf16 v[84:87], v[160:163], v[202:205], v[84:87]
	v_mfma_f32_16x16x32_bf16 v[80:83], v[168:171], v[202:205], v[80:83]
	v_mfma_f32_16x16x32_bf16 v[68:71], v[160:163], v[214:217], v[68:71]
	v_mfma_f32_16x16x32_bf16 v[64:67], v[168:171], v[214:217], v[64:67]
	v_mfma_f32_16x16x32_bf16 v[116:119], v[164:167], v[190:193], v[116:119]
	v_mfma_f32_16x16x32_bf16 v[112:115], v[182:185], v[190:193], v[112:115]
	v_mfma_f32_16x16x32_bf16 v[100:103], v[164:167], v[198:201], v[100:103]
	v_mfma_f32_16x16x32_bf16 v[96:99], v[182:185], v[198:201], v[96:99]
	v_mfma_f32_16x16x32_bf16 v[84:87], v[164:167], v[210:213], v[84:87]
	v_mfma_f32_16x16x32_bf16 v[80:83], v[182:185], v[210:213], v[80:83]
	v_mfma_f32_16x16x32_bf16 v[68:71], v[164:167], v[218:221], v[68:71]
	v_mfma_f32_16x16x32_bf16 v[64:67], v[182:185], v[218:221], v[64:67]
	s_setprio 0
	s_barrier
	s_add_i32 s48, s64, s23
	s_mov_b32 m0, s48
	ds_read_b128 v[186:189], v180 offset:49152
	ds_read_b128 v[190:193], v180 offset:50176
	ds_read_b128 v[194:197], v180 offset:51200
	ds_read_b128 v[198:201], v180 offset:52224
	ds_read_b128 v[202:205], v180 offset:53248
	ds_read_b128 v[210:213], v180 offset:54272
	ds_read_b128 v[214:217], v180 offset:55296
	ds_read_b128 v[218:221], v180 offset:56320
	global_load_lds_dwordx4 v130, s[98:99]
	s_add_i32 m0, s48, 0x2000
	s_add_u32 s46, s46, 0x40080
	s_addc_u32 s47, s47, 0
	s_add_i32 s48, s65, s23
	global_load_lds_dwordx4 v134, s[98:99]
	s_mov_b32 m0, s48
	s_nop 0
	global_load_lds_dwordx4 v130, s[46:47]
	s_add_i32 m0, s48, 0x2000
	s_nop 0
	global_load_lds_dwordx4 v134, s[46:47]
	s_mov_b32 m0, s54
	s_nop 0
	global_load_lds_dwordx4 v128, s[100:101]
	s_mov_b32 m0, s55
	s_nop 0
	global_load_lds_dwordx4 v132, s[100:101]
	s_waitcnt vmcnt(8)
	s_waitcnt lgkmcnt(0)
	s_barrier
	s_setprio 1
	s_waitcnt lgkmcnt(0)
	v_mfma_f32_16x16x32_bf16 v[60:63], v[144:147], v[186:189], v[60:63]
	v_mfma_f32_16x16x32_bf16 v[56:59], v[152:155], v[186:189], v[56:59]
	v_mfma_f32_16x16x32_bf16 v[44:47], v[144:147], v[194:197], v[44:47]
	v_mfma_f32_16x16x32_bf16 v[40:43], v[152:155], v[194:197], v[40:43]
	v_mfma_f32_16x16x32_bf16 v[28:31], v[144:147], v[202:205], v[28:31]
	v_mfma_f32_16x16x32_bf16 v[24:27], v[152:155], v[202:205], v[24:27]
	v_mfma_f32_16x16x32_bf16 v[12:15], v[144:147], v[214:217], v[12:15]
	v_mfma_f32_16x16x32_bf16 v[8:11], v[152:155], v[214:217], v[8:11]
	v_mfma_f32_16x16x32_bf16 v[60:63], v[148:151], v[190:193], v[60:63]
	v_mfma_f32_16x16x32_bf16 v[56:59], v[156:159], v[190:193], v[56:59]
	v_mfma_f32_16x16x32_bf16 v[44:47], v[148:151], v[198:201], v[44:47]
	v_mfma_f32_16x16x32_bf16 v[40:43], v[156:159], v[198:201], v[40:43]
	v_mfma_f32_16x16x32_bf16 v[28:31], v[148:151], v[210:213], v[28:31]
	v_mfma_f32_16x16x32_bf16 v[24:27], v[156:159], v[210:213], v[24:27]
	v_mfma_f32_16x16x32_bf16 v[12:15], v[148:151], v[218:221], v[12:15]
	v_mfma_f32_16x16x32_bf16 v[8:11], v[156:159], v[218:221], v[8:11]
	v_mfma_f32_16x16x32_bf16 v[52:55], v[160:163], v[186:189], v[52:55]
	v_mfma_f32_16x16x32_bf16 v[48:51], v[168:171], v[186:189], v[48:51]
	v_mfma_f32_16x16x32_bf16 v[36:39], v[160:163], v[194:197], v[36:39]
	v_mfma_f32_16x16x32_bf16 v[32:35], v[168:171], v[194:197], v[32:35]
	v_mfma_f32_16x16x32_bf16 v[20:23], v[160:163], v[202:205], v[20:23]
	v_mfma_f32_16x16x32_bf16 v[16:19], v[168:171], v[202:205], v[16:19]
	v_mfma_f32_16x16x32_bf16 v[4:7], v[160:163], v[214:217], v[4:7]
	v_mfma_f32_16x16x32_bf16 v[0:3], v[168:171], v[214:217], v[0:3]
	v_mfma_f32_16x16x32_bf16 v[52:55], v[164:167], v[190:193], v[52:55]
	v_mfma_f32_16x16x32_bf16 v[48:51], v[182:185], v[190:193], v[48:51]
	v_mfma_f32_16x16x32_bf16 v[36:39], v[164:167], v[198:201], v[36:39]
	v_mfma_f32_16x16x32_bf16 v[32:35], v[182:185], v[198:201], v[32:35]
	v_mfma_f32_16x16x32_bf16 v[20:23], v[164:167], v[210:213], v[20:23]
	v_mfma_f32_16x16x32_bf16 v[16:19], v[182:185], v[210:213], v[16:19]
	v_mfma_f32_16x16x32_bf16 v[4:7], v[164:167], v[218:221], v[4:7]
	v_mfma_f32_16x16x32_bf16 v[0:3], v[182:185], v[218:221], v[0:3]
	s_setprio 0
	s_barrier
	s_add_i32 s63, s63, 2
	s_add_u32 s44, s44, 0x100
	s_addc_u32 s45, s45, 0
	s_add_u32 s61, s61, 0x100
	s_addc_u32 s62, s62, 0
	s_cmp_gt_u32 s63, 13
	s_cbranch_scc0 .LBB0_245
	s_and_b64 vcc, exec, s[18:19]
	s_cbranch_vccz .LBB0_248
	s_barrier

.LBB0_492:
	ds_read_b128 v[128:131], v179
	ds_read_b128 v[132:135], v179 offset:1024
	ds_read_b128 v[136:139], v179 offset:2048
	ds_read_b128 v[140:143], v179 offset:3072
	ds_read_b128 v[144:147], v187
	ds_read_b128 v[148:151], v187 offset:1024
	ds_read_b128 v[180:183], v187 offset:2048
	ds_read_b128 v[188:191], v187 offset:3072
	s_add_u32 s48, s46, 0xfffc0080
	s_addc_u32 s49, s47, -1
	s_cmp_eq_u32 s66, 12
	s_cselect_b32 s51, s37, s49
	s_cselect_b32 s50, s43, s48
	s_cselect_b32 s49, s25, s65
	s_cselect_b32 s48, s63, s64
	s_add_i32 m0, s45, 0xc000
	ds_read_b128 v[196:199], v195
	ds_read_b128 v[202:205], v195 offset:1024
	ds_read_b128 v[210:213], v195 offset:2048
	ds_read_b128 v[214:217], v195 offset:3072
	ds_read_b128 v[218:221], v195 offset:4096
	ds_read_b128 v[222:225], v195 offset:5120
	ds_read_b128 v[226:229], v195 offset:6144
	ds_read_b128 v[230:233], v195 offset:7168
	global_load_lds_dwordx4 v160, s[46:47]
	s_add_i32 m0, s45, 0xe000
	s_nop 0
	global_load_lds_dwordx4 v162, s[46:47]
	s_waitcnt vmcnt(8)
	s_waitcnt lgkmcnt(0)
	s_barrier
	s_setprio 1
	s_waitcnt lgkmcnt(0)
	v_mfma_f32_16x16x32_bf16 v[124:127], v[128:131], v[196:199], v[124:127]
	v_mfma_f32_16x16x32_bf16 v[120:123], v[136:139], v[196:199], v[120:123]
	v_mfma_f32_16x16x32_bf16 v[108:111], v[128:131], v[210:213], v[108:111]
	v_mfma_f32_16x16x32_bf16 v[104:107], v[136:139], v[210:213], v[104:107]
	v_mfma_f32_16x16x32_bf16 v[92:95], v[128:131], v[218:221], v[92:95]
	v_mfma_f32_16x16x32_bf16 v[88:91], v[136:139], v[218:221], v[88:91]
	v_mfma_f32_16x16x32_bf16 v[76:79], v[128:131], v[226:229], v[76:79]
	v_mfma_f32_16x16x32_bf16 v[72:75], v[136:139], v[226:229], v[72:75]
	v_mfma_f32_16x16x32_bf16 v[124:127], v[132:135], v[202:205], v[124:127]
	v_mfma_f32_16x16x32_bf16 v[120:123], v[140:143], v[202:205], v[120:123]
	v_mfma_f32_16x16x32_bf16 v[108:111], v[132:135], v[214:217], v[108:111]
	v_mfma_f32_16x16x32_bf16 v[104:107], v[140:143], v[214:217], v[104:107]
	v_mfma_f32_16x16x32_bf16 v[92:95], v[132:135], v[222:225], v[92:95]
	v_mfma_f32_16x16x32_bf16 v[88:91], v[140:143], v[222:225], v[88:91]
	v_mfma_f32_16x16x32_bf16 v[76:79], v[132:135], v[230:233], v[76:79]
	v_mfma_f32_16x16x32_bf16 v[72:75], v[140:143], v[230:233], v[72:75]
	v_mfma_f32_16x16x32_bf16 v[116:119], v[144:147], v[196:199], v[116:119]
	v_mfma_f32_16x16x32_bf16 v[112:115], v[180:183], v[196:199], v[112:115]
	v_mfma_f32_16x16x32_bf16 v[100:103], v[144:147], v[210:213], v[100:103]
	v_mfma_f32_16x16x32_bf16 v[96:99], v[180:183], v[210:213], v[96:99]
	v_mfma_f32_16x16x32_bf16 v[84:87], v[144:147], v[218:221], v[84:87]
	v_mfma_f32_16x16x32_bf16 v[80:83], v[180:183], v[218:221], v[80:83]
	v_mfma_f32_16x16x32_bf16 v[68:71], v[144:147], v[226:229], v[68:71]
	v_mfma_f32_16x16x32_bf16 v[64:67], v[180:183], v[226:229], v[64:67]
	v_mfma_f32_16x16x32_bf16 v[116:119], v[148:151], v[202:205], v[116:119]
	v_mfma_f32_16x16x32_bf16 v[112:115], v[188:191], v[202:205], v[112:115]
	v_mfma_f32_16x16x32_bf16 v[100:103], v[148:151], v[214:217], v[100:103]
	v_mfma_f32_16x16x32_bf16 v[96:99], v[188:191], v[214:217], v[96:99]
	v_mfma_f32_16x16x32_bf16 v[84:87], v[148:151], v[222:225], v[84:87]
	v_mfma_f32_16x16x32_bf16 v[80:83], v[188:191], v[222:225], v[80:83]
	v_mfma_f32_16x16x32_bf16 v[68:71], v[148:151], v[230:233], v[68:71]
	v_mfma_f32_16x16x32_bf16 v[64:67], v[188:191], v[230:233], v[64:67]
	s_setprio 0
	s_barrier
	s_add_u32 s98, s48, s20
	s_addc_u32 s99, s49, s21
	s_add_u32 s100, s50, s20
	s_addc_u32 s101, s51, s21
	s_add_i32 s67, s61, s52
	s_mov_b32 m0, s67
	ds_read_b128 v[196:199], v195 offset:16384
	ds_read_b128 v[202:205], v195 offset:17408
	ds_read_b128 v[210:213], v195 offset:18432
	ds_read_b128 v[214:217], v195 offset:19456
	ds_read_b128 v[218:221], v195 offset:20480
	ds_read_b128 v[222:225], v195 offset:21504
	ds_read_b128 v[226:229], v195 offset:22528
	ds_read_b128 v[230:233], v195 offset:23552
	global_load_lds_dwordx4 v154, s[48:49]
	s_add_i32 m0, s67, 0x2000
	s_add_u32 s68, s48, 0x40000
	s_addc_u32 s69, s49, 0
	s_add_i32 s67, s62, s52
	global_load_lds_dwordx4 v158, s[48:49]
	s_mov_b32 m0, s67
	s_nop 0
	global_load_lds_dwordx4 v154, s[68:69]
	s_add_i32 m0, s67, 0x2000
	s_nop 0
	global_load_lds_dwordx4 v158, s[68:69]
	s_mov_b32 m0, s45
	s_nop 0
	global_load_lds_dwordx4 v152, s[50:51]
	s_mov_b32 m0, s53
	s_nop 0
	global_load_lds_dwordx4 v156, s[50:51]
	s_waitcnt vmcnt(8)
	s_waitcnt lgkmcnt(0)
	s_barrier
	s_setprio 1
	s_waitcnt lgkmcnt(0)
	v_mfma_f32_16x16x32_bf16 v[60:63], v[128:131], v[196:199], v[60:63]
	v_mfma_f32_16x16x32_bf16 v[56:59], v[136:139], v[196:199], v[56:59]
	v_mfma_f32_16x16x32_bf16 v[44:47], v[128:131], v[210:213], v[44:47]
	v_mfma_f32_16x16x32_bf16 v[40:43], v[136:139], v[210:213], v[40:43]
	v_mfma_f32_16x16x32_bf16 v[28:31], v[128:131], v[218:221], v[28:31]
	v_mfma_f32_16x16x32_bf16 v[24:27], v[136:139], v[218:221], v[24:27]
	v_mfma_f32_16x16x32_bf16 v[12:15], v[128:131], v[226:229], v[12:15]
	v_mfma_f32_16x16x32_bf16 v[8:11], v[136:139], v[226:229], v[8:11]
	v_mfma_f32_16x16x32_bf16 v[60:63], v[132:135], v[202:205], v[60:63]
	v_mfma_f32_16x16x32_bf16 v[56:59], v[140:143], v[202:205], v[56:59]
	v_mfma_f32_16x16x32_bf16 v[44:47], v[132:135], v[214:217], v[44:47]
	v_mfma_f32_16x16x32_bf16 v[40:43], v[140:143], v[214:217], v[40:43]
	v_mfma_f32_16x16x32_bf16 v[28:31], v[132:135], v[222:225], v[28:31]
	v_mfma_f32_16x16x32_bf16 v[24:27], v[140:143], v[222:225], v[24:27]
	v_mfma_f32_16x16x32_bf16 v[12:15], v[132:135], v[230:233], v[12:15]
	v_mfma_f32_16x16x32_bf16 v[8:11], v[140:143], v[230:233], v[8:11]
	v_mfma_f32_16x16x32_bf16 v[52:55], v[144:147], v[196:199], v[52:55]
	v_mfma_f32_16x16x32_bf16 v[48:51], v[180:183], v[196:199], v[48:51]
	v_mfma_f32_16x16x32_bf16 v[36:39], v[144:147], v[210:213], v[36:39]
	v_mfma_f32_16x16x32_bf16 v[32:35], v[180:183], v[210:213], v[32:35]
	v_mfma_f32_16x16x32_bf16 v[20:23], v[144:147], v[218:221], v[20:23]
	v_mfma_f32_16x16x32_bf16 v[16:19], v[180:183], v[218:221], v[16:19]
	v_mfma_f32_16x16x32_bf16 v[4:7], v[144:147], v[226:229], v[4:7]
	v_mfma_f32_16x16x32_bf16 v[0:3], v[180:183], v[226:229], v[0:3]
	v_mfma_f32_16x16x32_bf16 v[52:55], v[148:151], v[202:205], v[52:55]
	v_mfma_f32_16x16x32_bf16 v[48:51], v[188:191], v[202:205], v[48:51]
	v_mfma_f32_16x16x32_bf16 v[36:39], v[148:151], v[214:217], v[36:39]
	v_mfma_f32_16x16x32_bf16 v[32:35], v[188:191], v[214:217], v[32:35]
	v_mfma_f32_16x16x32_bf16 v[20:23], v[148:151], v[222:225], v[20:23]
	v_mfma_f32_16x16x32_bf16 v[16:19], v[188:191], v[222:225], v[16:19]
	v_mfma_f32_16x16x32_bf16 v[4:7], v[148:151], v[230:233], v[4:7]
	v_mfma_f32_16x16x32_bf16 v[0:3], v[188:191], v[230:233], v[0:3]
	s_setprio 0
	s_barrier
	s_add_i32 s67, 0, 0x18000
	s_add_i32 s68, 0, 0x1c000
	v_add_u32_e32 v140, s67, v173
	v_add_u32_e32 v170, s68, v173
	ds_read_b128 v[128:131], v140
	ds_read_b128 v[132:135], v140 offset:1024
	ds_read_b128 v[136:139], v140 offset:2048
	ds_read_b128 v[140:143], v140 offset:3072
	ds_read_b128 v[144:147], v170
	ds_read_b128 v[148:151], v170 offset:1024
	ds_read_b128 v[180:183], v170 offset:2048
	ds_read_b128 v[188:191], v170 offset:3072
	s_add_u32 s50, s50, 0x40000
	s_addc_u32 s51, s51, 0
	s_mov_b32 m0, s54
	ds_read_b128 v[196:199], v195 offset:32768
	ds_read_b128 v[202:205], v195 offset:33792
	ds_read_b128 v[210:213], v195 offset:34816
	ds_read_b128 v[214:217], v195 offset:35840
	ds_read_b128 v[218:221], v195 offset:36864
	ds_read_b128 v[222:225], v195 offset:37888
	ds_read_b128 v[226:229], v195 offset:38912
	ds_read_b128 v[230:233], v195 offset:39936
	global_load_lds_dwordx4 v152, s[50:51]
	s_mov_b32 m0, s55
	s_nop 0
	global_load_lds_dwordx4 v156, s[50:51]
	s_waitcnt vmcnt(8)
	s_waitcnt lgkmcnt(0)
	s_barrier
	s_setprio 1
	s_waitcnt lgkmcnt(0)
	v_mfma_f32_16x16x32_bf16 v[124:127], v[128:131], v[196:199], v[124:127]
	v_mfma_f32_16x16x32_bf16 v[120:123], v[136:139], v[196:199], v[120:123]
	v_mfma_f32_16x16x32_bf16 v[108:111], v[128:131], v[210:213], v[108:111]
	v_mfma_f32_16x16x32_bf16 v[104:107], v[136:139], v[210:213], v[104:107]
	v_mfma_f32_16x16x32_bf16 v[92:95], v[128:131], v[218:221], v[92:95]
	v_mfma_f32_16x16x32_bf16 v[88:91], v[136:139], v[218:221], v[88:91]
	v_mfma_f32_16x16x32_bf16 v[76:79], v[128:131], v[226:229], v[76:79]
	v_mfma_f32_16x16x32_bf16 v[72:75], v[136:139], v[226:229], v[72:75]
	v_mfma_f32_16x16x32_bf16 v[124:127], v[132:135], v[202:205], v[124:127]
	v_mfma_f32_16x16x32_bf16 v[120:123], v[140:143], v[202:205], v[120:123]
	v_mfma_f32_16x16x32_bf16 v[108:111], v[132:135], v[214:217], v[108:111]
	v_mfma_f32_16x16x32_bf16 v[104:107], v[140:143], v[214:217], v[104:107]
	v_mfma_f32_16x16x32_bf16 v[92:95], v[132:135], v[222:225], v[92:95]
	v_mfma_f32_16x16x32_bf16 v[88:91], v[140:143], v[222:225], v[88:91]
	v_mfma_f32_16x16x32_bf16 v[76:79], v[132:135], v[230:233], v[76:79]
	v_mfma_f32_16x16x32_bf16 v[72:75], v[140:143], v[230:233], v[72:75]
	v_mfma_f32_16x16x32_bf16 v[116:119], v[144:147], v[196:199], v[116:119]
	v_mfma_f32_16x16x32_bf16 v[112:115], v[180:183], v[196:199], v[112:115]
	v_mfma_f32_16x16x32_bf16 v[100:103], v[144:147], v[210:213], v[100:103]
	v_mfma_f32_16x16x32_bf16 v[96:99], v[180:183], v[210:213], v[96:99]
	v_mfma_f32_16x16x32_bf16 v[84:87], v[144:147], v[218:221], v[84:87]
	v_mfma_f32_16x16x32_bf16 v[80:83], v[180:183], v[218:221], v[80:83]
	v_mfma_f32_16x16x32_bf16 v[68:71], v[144:147], v[226:229], v[68:71]
	v_mfma_f32_16x16x32_bf16 v[64:67], v[180:183], v[226:229], v[64:67]
	v_mfma_f32_16x16x32_bf16 v[116:119], v[148:151], v[202:205], v[116:119]
	v_mfma_f32_16x16x32_bf16 v[112:115], v[188:191], v[202:205], v[112:115]
	v_mfma_f32_16x16x32_bf16 v[100:103], v[148:151], v[214:217], v[100:103]
	v_mfma_f32_16x16x32_bf16 v[96:99], v[188:191], v[214:217], v[96:99]
	v_mfma_f32_16x16x32_bf16 v[84:87], v[148:151], v[222:225], v[84:87]
	v_mfma_f32_16x16x32_bf16 v[80:83], v[188:191], v[222:225], v[80:83]
	v_mfma_f32_16x16x32_bf16 v[68:71], v[148:151], v[230:233], v[68:71]
	v_mfma_f32_16x16x32_bf16 v[64:67], v[188:191], v[230:233], v[64:67]
	s_setprio 0
	s_barrier
	s_add_i32 s50, s67, s52
	s_mov_b32 m0, s50
	ds_read_b128 v[196:199], v195 offset:49152
	ds_read_b128 v[202:205], v195 offset:50176
	ds_read_b128 v[210:213], v195 offset:51200
	ds_read_b128 v[214:217], v195 offset:52224
	ds_read_b128 v[218:221], v195 offset:53248
	ds_read_b128 v[222:225], v195 offset:54272
	ds_read_b128 v[226:229], v195 offset:55296
	ds_read_b128 v[230:233], v195 offset:56320
	global_load_lds_dwordx4 v154, s[98:99]
	s_add_i32 m0, s50, 0x2000
	s_add_u32 s48, s48, 0x40080
	s_addc_u32 s49, s49, 0
	s_add_i32 s50, s68, s52
	global_load_lds_dwordx4 v158, s[98:99]
	s_mov_b32 m0, s50
	s_nop 0
	global_load_lds_dwordx4 v154, s[48:49]
	s_add_i32 m0, s50, 0x2000
	s_nop 0
	global_load_lds_dwordx4 v158, s[48:49]
	s_mov_b32 m0, s57
	s_nop 0
	global_load_lds_dwordx4 v152, s[100:101]
	s_mov_b32 m0, s58
	s_nop 0
	global_load_lds_dwordx4 v156, s[100:101]
	s_waitcnt vmcnt(8)
	s_waitcnt lgkmcnt(0)
	s_barrier
	s_setprio 1
	s_waitcnt lgkmcnt(0)
	v_mfma_f32_16x16x32_bf16 v[60:63], v[128:131], v[196:199], v[60:63]
	v_mfma_f32_16x16x32_bf16 v[56:59], v[136:139], v[196:199], v[56:59]
	v_mfma_f32_16x16x32_bf16 v[44:47], v[128:131], v[210:213], v[44:47]
	v_mfma_f32_16x16x32_bf16 v[40:43], v[136:139], v[210:213], v[40:43]
	v_mfma_f32_16x16x32_bf16 v[28:31], v[128:131], v[218:221], v[28:31]
	v_mfma_f32_16x16x32_bf16 v[24:27], v[136:139], v[218:221], v[24:27]
	v_mfma_f32_16x16x32_bf16 v[12:15], v[128:131], v[226:229], v[12:15]
	v_mfma_f32_16x16x32_bf16 v[8:11], v[136:139], v[226:229], v[8:11]
	v_mfma_f32_16x16x32_bf16 v[60:63], v[132:135], v[202:205], v[60:63]
	v_mfma_f32_16x16x32_bf16 v[56:59], v[140:143], v[202:205], v[56:59]
	v_mfma_f32_16x16x32_bf16 v[44:47], v[132:135], v[214:217], v[44:47]
	v_mfma_f32_16x16x32_bf16 v[40:43], v[140:143], v[214:217], v[40:43]
	v_mfma_f32_16x16x32_bf16 v[28:31], v[132:135], v[222:225], v[28:31]
	v_mfma_f32_16x16x32_bf16 v[24:27], v[140:143], v[222:225], v[24:27]
	v_mfma_f32_16x16x32_bf16 v[12:15], v[132:135], v[230:233], v[12:15]
	v_mfma_f32_16x16x32_bf16 v[8:11], v[140:143], v[230:233], v[8:11]
	v_mfma_f32_16x16x32_bf16 v[52:55], v[144:147], v[196:199], v[52:55]
	v_mfma_f32_16x16x32_bf16 v[48:51], v[180:183], v[196:199], v[48:51]
	v_mfma_f32_16x16x32_bf16 v[36:39], v[144:147], v[210:213], v[36:39]
	v_mfma_f32_16x16x32_bf16 v[32:35], v[180:183], v[210:213], v[32:35]
	v_mfma_f32_16x16x32_bf16 v[20:23], v[144:147], v[218:221], v[20:23]
	v_mfma_f32_16x16x32_bf16 v[16:19], v[180:183], v[218:221], v[16:19]
	v_mfma_f32_16x16x32_bf16 v[4:7], v[144:147], v[226:229], v[4:7]
	v_mfma_f32_16x16x32_bf16 v[0:3], v[180:183], v[226:229], v[0:3]
	v_mfma_f32_16x16x32_bf16 v[52:55], v[148:151], v[202:205], v[52:55]
	v_mfma_f32_16x16x32_bf16 v[48:51], v[188:191], v[202:205], v[48:51]
	v_mfma_f32_16x16x32_bf16 v[36:39], v[148:151], v[214:217], v[36:39]
	v_mfma_f32_16x16x32_bf16 v[32:35], v[188:191], v[214:217], v[32:35]
	v_mfma_f32_16x16x32_bf16 v[20:23], v[148:151], v[222:225], v[20:23]
	v_mfma_f32_16x16x32_bf16 v[16:19], v[188:191], v[222:225], v[16:19]
	v_mfma_f32_16x16x32_bf16 v[4:7], v[148:151], v[230:233], v[4:7]
	v_mfma_f32_16x16x32_bf16 v[0:3], v[188:191], v[230:233], v[0:3]
	s_setprio 0
	s_barrier
	s_add_i32 s66, s66, 2
	s_add_u32 s46, s46, 0x100
	s_addc_u32 s47, s47, 0
	s_add_u32 s64, s64, 0x100
	s_addc_u32 s65, s65, 0
	s_cmp_gt_u32 s66, 13
	s_cbranch_scc0 .LBB0_492
	s_and_b64 vcc, exec, s[22:23]
	s_cbranch_vccz .LBB0_495
	s_barrier

.LBB0_578:
	ds_read_b128 v[72:75], v206
	ds_read_b128 v[76:79], v206 offset:1024
	ds_read_b128 v[80:83], v206 offset:2048
	ds_read_b128 v[84:87], v206 offset:3072
	ds_read_b128 v[116:119], v207
	ds_read_b128 v[120:123], v207 offset:1024
	ds_read_b128 v[124:127], v207 offset:2048
	ds_read_b128 v[128:131], v207 offset:3072
	s_add_u32 s58, s56, 0x100
	s_addc_u32 s59, s57, 0
	s_cmp_eq_u32 s79, 12
	s_cselect_b32 s63, s47, s59
	s_cselect_b32 s62, s53, s58
	s_cselect_b32 s61, s45, s78
	s_cselect_b32 s60, s76, s77
	s_add_i32 m0, s43, 0xc000
	ds_read_b128 v[140:143], v209
	ds_read_b128 v[164:167], v209 offset:1024
	ds_read_b128 v[168:171], v209 offset:2048
	ds_read_b128 v[192:195], v209 offset:3072
	ds_read_b128 v[196:199], v209 offset:4096
	ds_read_b128 v[200:203], v209 offset:5120
	ds_read_b128 v[212:215], v209 offset:6144
	ds_read_b128 v[216:219], v209 offset:7168
	global_load_lds_dwordx4 v184, s[56:57]
	s_add_i32 m0, s43, 0xe000
	s_nop 0
	global_load_lds_dwordx4 v186, s[56:57]
	s_waitcnt vmcnt(8)
	s_waitcnt lgkmcnt(0)
	s_barrier
	s_setprio 1
	s_waitcnt lgkmcnt(0)
	v_mfma_f32_16x16x32_bf16 v[160:163], v[72:75], v[140:143], v[160:163]
	v_mfma_f32_16x16x32_bf16 v[108:111], v[80:83], v[140:143], v[108:111]
	v_mfma_f32_16x16x32_bf16 v[156:159], v[72:75], v[168:171], v[156:159]
	v_mfma_f32_16x16x32_bf16 v[104:107], v[80:83], v[168:171], v[104:107]
	v_mfma_f32_16x16x32_bf16 v[144:147], v[72:75], v[196:199], v[144:147]
	v_mfma_f32_16x16x32_bf16 v[92:95], v[80:83], v[196:199], v[92:95]
	v_mfma_f32_16x16x32_bf16 v[152:155], v[72:75], v[212:215], v[152:155]
	v_mfma_f32_16x16x32_bf16 v[100:103], v[80:83], v[212:215], v[100:103]
	v_mfma_f32_16x16x32_bf16 v[160:163], v[76:79], v[164:167], v[160:163]
	v_mfma_f32_16x16x32_bf16 v[108:111], v[84:87], v[164:167], v[108:111]
	v_mfma_f32_16x16x32_bf16 v[156:159], v[76:79], v[192:195], v[156:159]
	v_mfma_f32_16x16x32_bf16 v[104:107], v[84:87], v[192:195], v[104:107]
	v_mfma_f32_16x16x32_bf16 v[144:147], v[76:79], v[200:203], v[144:147]
	v_mfma_f32_16x16x32_bf16 v[92:95], v[84:87], v[200:203], v[92:95]
	v_mfma_f32_16x16x32_bf16 v[152:155], v[76:79], v[216:219], v[152:155]
	v_mfma_f32_16x16x32_bf16 v[100:103], v[84:87], v[216:219], v[100:103]
	v_mfma_f32_16x16x32_bf16 v[148:151], v[116:119], v[140:143], v[148:151]
	v_mfma_f32_16x16x32_bf16 v[96:99], v[124:127], v[140:143], v[96:99]
	v_mfma_f32_16x16x32_bf16 v[136:139], v[116:119], v[168:171], v[136:139]
	v_mfma_f32_16x16x32_bf16 v[88:91], v[124:127], v[168:171], v[88:91]
	v_mfma_f32_16x16x32_bf16 v[132:135], v[116:119], v[196:199], v[132:135]
	v_mfma_f32_16x16x32_bf16 v[68:71], v[124:127], v[196:199], v[68:71]
	v_mfma_f32_16x16x32_bf16 v[112:115], v[116:119], v[212:215], v[112:115]
	v_mfma_f32_16x16x32_bf16 v[64:67], v[124:127], v[212:215], v[64:67]
	v_mfma_f32_16x16x32_bf16 v[148:151], v[120:123], v[164:167], v[148:151]
	v_mfma_f32_16x16x32_bf16 v[96:99], v[128:131], v[164:167], v[96:99]
	v_mfma_f32_16x16x32_bf16 v[136:139], v[120:123], v[192:195], v[136:139]
	v_mfma_f32_16x16x32_bf16 v[88:91], v[128:131], v[192:195], v[88:91]
	v_mfma_f32_16x16x32_bf16 v[132:135], v[120:123], v[200:203], v[132:135]
	v_mfma_f32_16x16x32_bf16 v[68:71], v[128:131], v[200:203], v[68:71]
	v_mfma_f32_16x16x32_bf16 v[112:115], v[120:123], v[216:219], v[112:115]
	v_mfma_f32_16x16x32_bf16 v[64:67], v[128:131], v[216:219], v[64:67]
	s_setprio 0
	s_barrier
	s_add_u32 s98, s60, s22
	s_addc_u32 s99, s61, s23
	s_add_u32 s100, s62, s22
	s_addc_u32 s101, s63, s23
	s_add_i32 s56, s73, s41
	s_mov_b32 m0, s56
	ds_read_b128 v[140:143], v209 offset:16384
	ds_read_b128 v[164:167], v209 offset:17408
	ds_read_b128 v[168:171], v209 offset:18432
	ds_read_b128 v[192:195], v209 offset:19456
	ds_read_b128 v[196:199], v209 offset:20480
	ds_read_b128 v[200:203], v209 offset:21504
	ds_read_b128 v[212:215], v209 offset:22528
	ds_read_b128 v[216:219], v209 offset:23552
	global_load_lds_dwordx4 v176, s[60:61]
	s_add_i32 m0, s56, 0x2000
	s_add_u32 s56, s60, 0x40000
	s_addc_u32 s57, s61, 0
	s_add_i32 s80, s74, s41
	global_load_lds_dwordx4 v180, s[60:61]
	s_mov_b32 m0, s80
	s_nop 0
	global_load_lds_dwordx4 v176, s[56:57]
	s_add_i32 m0, s80, 0x2000
	s_nop 0
	global_load_lds_dwordx4 v180, s[56:57]
	s_mov_b32 m0, s43
	s_nop 0
	global_load_lds_dwordx4 v174, s[62:63]
	s_mov_b32 m0, s55
	s_nop 0
	global_load_lds_dwordx4 v178, s[62:63]
	s_waitcnt vmcnt(8)
	s_waitcnt lgkmcnt(0)
	s_barrier
	s_setprio 1
	s_waitcnt lgkmcnt(0)
	v_mfma_f32_16x16x32_bf16 v[60:63], v[72:75], v[140:143], v[60:63]
	v_mfma_f32_16x16x32_bf16 v[28:31], v[80:83], v[140:143], v[28:31]
	v_mfma_f32_16x16x32_bf16 v[56:59], v[72:75], v[168:171], v[56:59]
	v_mfma_f32_16x16x32_bf16 v[24:27], v[80:83], v[168:171], v[24:27]
	v_mfma_f32_16x16x32_bf16 v[44:47], v[72:75], v[196:199], v[44:47]
	v_mfma_f32_16x16x32_bf16 v[12:15], v[80:83], v[196:199], v[12:15]
	v_mfma_f32_16x16x32_bf16 v[52:55], v[72:75], v[212:215], v[52:55]
	v_mfma_f32_16x16x32_bf16 v[20:23], v[80:83], v[212:215], v[20:23]
	v_mfma_f32_16x16x32_bf16 v[60:63], v[76:79], v[164:167], v[60:63]
	v_mfma_f32_16x16x32_bf16 v[28:31], v[84:87], v[164:167], v[28:31]
	v_mfma_f32_16x16x32_bf16 v[56:59], v[76:79], v[192:195], v[56:59]
	v_mfma_f32_16x16x32_bf16 v[24:27], v[84:87], v[192:195], v[24:27]
	v_mfma_f32_16x16x32_bf16 v[44:47], v[76:79], v[200:203], v[44:47]
	v_mfma_f32_16x16x32_bf16 v[12:15], v[84:87], v[200:203], v[12:15]
	v_mfma_f32_16x16x32_bf16 v[52:55], v[76:79], v[216:219], v[52:55]
	v_mfma_f32_16x16x32_bf16 v[20:23], v[84:87], v[216:219], v[20:23]
	v_mfma_f32_16x16x32_bf16 v[48:51], v[116:119], v[140:143], v[48:51]
	v_mfma_f32_16x16x32_bf16 v[16:19], v[124:127], v[140:143], v[16:19]
	v_mfma_f32_16x16x32_bf16 v[40:43], v[116:119], v[168:171], v[40:43]
	v_mfma_f32_16x16x32_bf16 v[8:11], v[124:127], v[168:171], v[8:11]
	v_mfma_f32_16x16x32_bf16 v[36:39], v[116:119], v[196:199], v[36:39]
	v_mfma_f32_16x16x32_bf16 v[4:7], v[124:127], v[196:199], v[4:7]
	v_mfma_f32_16x16x32_bf16 v[32:35], v[116:119], v[212:215], v[32:35]
	v_mfma_f32_16x16x32_bf16 v[0:3], v[124:127], v[212:215], v[0:3]
	v_mfma_f32_16x16x32_bf16 v[48:51], v[120:123], v[164:167], v[48:51]
	v_mfma_f32_16x16x32_bf16 v[16:19], v[128:131], v[164:167], v[16:19]
	v_mfma_f32_16x16x32_bf16 v[40:43], v[120:123], v[192:195], v[40:43]
	v_mfma_f32_16x16x32_bf16 v[8:11], v[128:131], v[192:195], v[8:11]
	v_mfma_f32_16x16x32_bf16 v[36:39], v[120:123], v[200:203], v[36:39]
	v_mfma_f32_16x16x32_bf16 v[4:7], v[128:131], v[200:203], v[4:7]
	v_mfma_f32_16x16x32_bf16 v[32:35], v[120:123], v[216:219], v[32:35]
	v_mfma_f32_16x16x32_bf16 v[0:3], v[128:131], v[216:219], v[0:3]
	s_setprio 0
	s_barrier
	s_add_i32 s80, 0, 0x18000
	s_add_i32 s81, 0, 0x1c000
	v_add_u32_e32 v84, s80, v204
	v_add_u32_e32 v128, s81, v204
	ds_read_b128 v[72:75], v84
	ds_read_b128 v[76:79], v84 offset:1024
	ds_read_b128 v[80:83], v84 offset:2048
	ds_read_b128 v[84:87], v84 offset:3072
	ds_read_b128 v[116:119], v128
	ds_read_b128 v[120:123], v128 offset:1024
	ds_read_b128 v[124:127], v128 offset:2048
	ds_read_b128 v[128:131], v128 offset:3072
	s_add_u32 s56, s62, 0x40000
	s_addc_u32 s57, s63, 0
	s_mov_b32 m0, s64
	ds_read_b128 v[140:143], v209 offset:32768
	ds_read_b128 v[164:167], v209 offset:33792
	ds_read_b128 v[168:171], v209 offset:34816
	ds_read_b128 v[192:195], v209 offset:35840
	ds_read_b128 v[196:199], v209 offset:36864
	ds_read_b128 v[200:203], v209 offset:37888
	ds_read_b128 v[212:215], v209 offset:38912
	ds_read_b128 v[216:219], v209 offset:39936
	global_load_lds_dwordx4 v174, s[56:57]
	s_mov_b32 m0, s65
	s_nop 0
	global_load_lds_dwordx4 v178, s[56:57]
	s_waitcnt vmcnt(8)
	s_waitcnt lgkmcnt(0)
	s_barrier
	s_setprio 1
	s_waitcnt lgkmcnt(0)
	v_mfma_f32_16x16x32_bf16 v[160:163], v[72:75], v[140:143], v[160:163]
	v_mfma_f32_16x16x32_bf16 v[108:111], v[80:83], v[140:143], v[108:111]
	v_mfma_f32_16x16x32_bf16 v[156:159], v[72:75], v[168:171], v[156:159]
	v_mfma_f32_16x16x32_bf16 v[104:107], v[80:83], v[168:171], v[104:107]
	v_mfma_f32_16x16x32_bf16 v[144:147], v[72:75], v[196:199], v[144:147]
	v_mfma_f32_16x16x32_bf16 v[92:95], v[80:83], v[196:199], v[92:95]
	v_mfma_f32_16x16x32_bf16 v[152:155], v[72:75], v[212:215], v[152:155]
	v_mfma_f32_16x16x32_bf16 v[100:103], v[80:83], v[212:215], v[100:103]
	v_mfma_f32_16x16x32_bf16 v[160:163], v[76:79], v[164:167], v[160:163]
	v_mfma_f32_16x16x32_bf16 v[108:111], v[84:87], v[164:167], v[108:111]
	v_mfma_f32_16x16x32_bf16 v[156:159], v[76:79], v[192:195], v[156:159]
	v_mfma_f32_16x16x32_bf16 v[104:107], v[84:87], v[192:195], v[104:107]
	v_mfma_f32_16x16x32_bf16 v[144:147], v[76:79], v[200:203], v[144:147]
	v_mfma_f32_16x16x32_bf16 v[92:95], v[84:87], v[200:203], v[92:95]
	v_mfma_f32_16x16x32_bf16 v[152:155], v[76:79], v[216:219], v[152:155]
	v_mfma_f32_16x16x32_bf16 v[100:103], v[84:87], v[216:219], v[100:103]
	v_mfma_f32_16x16x32_bf16 v[148:151], v[116:119], v[140:143], v[148:151]
	v_mfma_f32_16x16x32_bf16 v[96:99], v[124:127], v[140:143], v[96:99]
	v_mfma_f32_16x16x32_bf16 v[136:139], v[116:119], v[168:171], v[136:139]
	v_mfma_f32_16x16x32_bf16 v[88:91], v[124:127], v[168:171], v[88:91]
	v_mfma_f32_16x16x32_bf16 v[132:135], v[116:119], v[196:199], v[132:135]
	v_mfma_f32_16x16x32_bf16 v[68:71], v[124:127], v[196:199], v[68:71]
	v_mfma_f32_16x16x32_bf16 v[112:115], v[116:119], v[212:215], v[112:115]
	v_mfma_f32_16x16x32_bf16 v[64:67], v[124:127], v[212:215], v[64:67]
	v_mfma_f32_16x16x32_bf16 v[148:151], v[120:123], v[164:167], v[148:151]
	v_mfma_f32_16x16x32_bf16 v[96:99], v[128:131], v[164:167], v[96:99]
	v_mfma_f32_16x16x32_bf16 v[136:139], v[120:123], v[192:195], v[136:139]
	v_mfma_f32_16x16x32_bf16 v[88:91], v[128:131], v[192:195], v[88:91]
	v_mfma_f32_16x16x32_bf16 v[132:135], v[120:123], v[200:203], v[132:135]
	v_mfma_f32_16x16x32_bf16 v[68:71], v[128:131], v[200:203], v[68:71]
	v_mfma_f32_16x16x32_bf16 v[112:115], v[120:123], v[216:219], v[112:115]
	v_mfma_f32_16x16x32_bf16 v[64:67], v[128:131], v[216:219], v[64:67]
	s_setprio 0
	s_barrier
	s_add_i32 s56, s80, s41
	s_mov_b32 m0, s56
	ds_read_b128 v[140:143], v209 offset:49152
	ds_read_b128 v[164:167], v209 offset:50176
	ds_read_b128 v[168:171], v209 offset:51200
	ds_read_b128 v[192:195], v209 offset:52224
	ds_read_b128 v[196:199], v209 offset:53248
	ds_read_b128 v[200:203], v209 offset:54272
	ds_read_b128 v[212:215], v209 offset:55296
	ds_read_b128 v[216:219], v209 offset:56320
	global_load_lds_dwordx4 v176, s[98:99]
	s_add_i32 m0, s56, 0x2000
	s_add_u32 s56, s60, 0x40080
	s_addc_u32 s57, s61, 0
	s_add_i32 s60, s81, s41
	global_load_lds_dwordx4 v180, s[98:99]
	s_mov_b32 m0, s60
	s_nop 0
	global_load_lds_dwordx4 v176, s[56:57]
	s_add_i32 m0, s60, 0x2000
	s_nop 0
	global_load_lds_dwordx4 v180, s[56:57]
	s_mov_b32 m0, s69
	s_nop 0
	global_load_lds_dwordx4 v174, s[100:101]
	s_mov_b32 m0, s70
	s_nop 0
	global_load_lds_dwordx4 v178, s[100:101]
	s_waitcnt vmcnt(8)
	s_waitcnt lgkmcnt(0)
	s_barrier
	s_setprio 1
	s_waitcnt lgkmcnt(0)
	v_mfma_f32_16x16x32_bf16 v[60:63], v[72:75], v[140:143], v[60:63]
	v_mfma_f32_16x16x32_bf16 v[28:31], v[80:83], v[140:143], v[28:31]
	v_mfma_f32_16x16x32_bf16 v[56:59], v[72:75], v[168:171], v[56:59]
	v_mfma_f32_16x16x32_bf16 v[24:27], v[80:83], v[168:171], v[24:27]
	v_mfma_f32_16x16x32_bf16 v[44:47], v[72:75], v[196:199], v[44:47]
	v_mfma_f32_16x16x32_bf16 v[12:15], v[80:83], v[196:199], v[12:15]
	v_mfma_f32_16x16x32_bf16 v[52:55], v[72:75], v[212:215], v[52:55]
	v_mfma_f32_16x16x32_bf16 v[20:23], v[80:83], v[212:215], v[20:23]
	v_mfma_f32_16x16x32_bf16 v[60:63], v[76:79], v[164:167], v[60:63]
	v_mfma_f32_16x16x32_bf16 v[28:31], v[84:87], v[164:167], v[28:31]
	v_mfma_f32_16x16x32_bf16 v[56:59], v[76:79], v[192:195], v[56:59]
	v_mfma_f32_16x16x32_bf16 v[24:27], v[84:87], v[192:195], v[24:27]
	v_mfma_f32_16x16x32_bf16 v[44:47], v[76:79], v[200:203], v[44:47]
	v_mfma_f32_16x16x32_bf16 v[12:15], v[84:87], v[200:203], v[12:15]
	v_mfma_f32_16x16x32_bf16 v[52:55], v[76:79], v[216:219], v[52:55]
	v_mfma_f32_16x16x32_bf16 v[20:23], v[84:87], v[216:219], v[20:23]
	v_mfma_f32_16x16x32_bf16 v[48:51], v[116:119], v[140:143], v[48:51]
	v_mfma_f32_16x16x32_bf16 v[16:19], v[124:127], v[140:143], v[16:19]
	v_mfma_f32_16x16x32_bf16 v[40:43], v[116:119], v[168:171], v[40:43]
	v_mfma_f32_16x16x32_bf16 v[8:11], v[124:127], v[168:171], v[8:11]
	v_mfma_f32_16x16x32_bf16 v[36:39], v[116:119], v[196:199], v[36:39]
	v_mfma_f32_16x16x32_bf16 v[4:7], v[124:127], v[196:199], v[4:7]
	v_mfma_f32_16x16x32_bf16 v[32:35], v[116:119], v[212:215], v[32:35]
	v_mfma_f32_16x16x32_bf16 v[0:3], v[124:127], v[212:215], v[0:3]
	v_mfma_f32_16x16x32_bf16 v[48:51], v[120:123], v[164:167], v[48:51]
	v_mfma_f32_16x16x32_bf16 v[16:19], v[128:131], v[164:167], v[16:19]
	v_mfma_f32_16x16x32_bf16 v[40:43], v[120:123], v[192:195], v[40:43]
	v_mfma_f32_16x16x32_bf16 v[8:11], v[128:131], v[192:195], v[8:11]
	v_mfma_f32_16x16x32_bf16 v[36:39], v[120:123], v[200:203], v[36:39]
	v_mfma_f32_16x16x32_bf16 v[4:7], v[128:131], v[200:203], v[4:7]
	v_mfma_f32_16x16x32_bf16 v[32:35], v[120:123], v[216:219], v[32:35]
	v_mfma_f32_16x16x32_bf16 v[0:3], v[128:131], v[216:219], v[0:3]
	s_setprio 0
	s_barrier
	s_add_i32 s79, s79, 2
	s_add_u32 s77, s77, 0x100
	s_addc_u32 s78, s78, 0
	s_cmp_gt_u32 s79, 13
	s_mov_b64 s[56:57], s[58:59]
	s_cbranch_scc0 .LBB0_578
	s_and_b64 vcc, exec, s[24:25]
	s_cbranch_vccz .LBB0_581
	s_barrier

.LBB0_741:
	ds_read_b128 v[128:131], v194
	ds_read_b128 v[132:135], v194 offset:1024
	ds_read_b128 v[136:139], v194 offset:2048
	ds_read_b128 v[140:143], v194 offset:3072
	ds_read_b128 v[144:147], v195
	ds_read_b128 v[148:151], v195 offset:1024
	ds_read_b128 v[168:171], v195 offset:2048
	ds_read_b128 v[174:177], v195 offset:3072
	s_add_u32 s38, s36, 0x100
	s_addc_u32 s39, s37, 0
	s_cmp_eq_u32 s62, 40
	s_cselect_b32 s43, s11, s39
	s_cselect_b32 s42, s10, s38
	s_cselect_b32 s41, s25, s61
	s_cselect_b32 s40, s24, s60
	s_add_i32 m0, s45, 0xc000
	ds_read_b128 v[178:181], v196
	ds_read_b128 v[182:185], v196 offset:1024
	ds_read_b128 v[186:189], v196 offset:2048
	ds_read_b128 v[198:201], v196 offset:3072
	ds_read_b128 v[202:205], v196 offset:4096
	ds_read_b128 v[210:213], v196 offset:5120
	ds_read_b128 v[214:217], v196 offset:6144
	ds_read_b128 v[218:221], v196 offset:7168
	global_load_lds_dwordx4 v160, s[36:37]
	s_add_i32 m0, s45, 0xe000
	s_nop 0
	global_load_lds_dwordx4 v162, s[36:37]
	s_waitcnt vmcnt(8)
	s_waitcnt lgkmcnt(0)
	s_barrier
	s_setprio 1
	s_waitcnt lgkmcnt(0)
	v_mfma_f32_16x16x32_bf16 v[124:127], v[128:131], v[178:181], v[124:127]
	v_mfma_f32_16x16x32_bf16 v[120:123], v[136:139], v[178:181], v[120:123]
	v_mfma_f32_16x16x32_bf16 v[108:111], v[128:131], v[186:189], v[108:111]
	v_mfma_f32_16x16x32_bf16 v[104:107], v[136:139], v[186:189], v[104:107]
	v_mfma_f32_16x16x32_bf16 v[92:95], v[128:131], v[202:205], v[92:95]
	v_mfma_f32_16x16x32_bf16 v[88:91], v[136:139], v[202:205], v[88:91]
	v_mfma_f32_16x16x32_bf16 v[76:79], v[128:131], v[214:217], v[76:79]
	v_mfma_f32_16x16x32_bf16 v[72:75], v[136:139], v[214:217], v[72:75]
	v_mfma_f32_16x16x32_bf16 v[124:127], v[132:135], v[182:185], v[124:127]
	v_mfma_f32_16x16x32_bf16 v[120:123], v[140:143], v[182:185], v[120:123]
	v_mfma_f32_16x16x32_bf16 v[108:111], v[132:135], v[198:201], v[108:111]
	v_mfma_f32_16x16x32_bf16 v[104:107], v[140:143], v[198:201], v[104:107]
	v_mfma_f32_16x16x32_bf16 v[92:95], v[132:135], v[210:213], v[92:95]
	v_mfma_f32_16x16x32_bf16 v[88:91], v[140:143], v[210:213], v[88:91]
	v_mfma_f32_16x16x32_bf16 v[76:79], v[132:135], v[218:221], v[76:79]
	v_mfma_f32_16x16x32_bf16 v[72:75], v[140:143], v[218:221], v[72:75]
	v_mfma_f32_16x16x32_bf16 v[116:119], v[144:147], v[178:181], v[116:119]
	v_mfma_f32_16x16x32_bf16 v[112:115], v[168:171], v[178:181], v[112:115]
	v_mfma_f32_16x16x32_bf16 v[100:103], v[144:147], v[186:189], v[100:103]
	v_mfma_f32_16x16x32_bf16 v[96:99], v[168:171], v[186:189], v[96:99]
	v_mfma_f32_16x16x32_bf16 v[84:87], v[144:147], v[202:205], v[84:87]
	v_mfma_f32_16x16x32_bf16 v[80:83], v[168:171], v[202:205], v[80:83]
	v_mfma_f32_16x16x32_bf16 v[68:71], v[144:147], v[214:217], v[68:71]
	v_mfma_f32_16x16x32_bf16 v[64:67], v[168:171], v[214:217], v[64:67]
	v_mfma_f32_16x16x32_bf16 v[116:119], v[148:151], v[182:185], v[116:119]
	v_mfma_f32_16x16x32_bf16 v[112:115], v[174:177], v[182:185], v[112:115]
	v_mfma_f32_16x16x32_bf16 v[100:103], v[148:151], v[198:201], v[100:103]
	v_mfma_f32_16x16x32_bf16 v[96:99], v[174:177], v[198:201], v[96:99]
	v_mfma_f32_16x16x32_bf16 v[84:87], v[148:151], v[210:213], v[84:87]
	v_mfma_f32_16x16x32_bf16 v[80:83], v[174:177], v[210:213], v[80:83]
	v_mfma_f32_16x16x32_bf16 v[68:71], v[148:151], v[218:221], v[68:71]
	v_mfma_f32_16x16x32_bf16 v[64:67], v[174:177], v[218:221], v[64:67]
	s_setprio 0
	s_barrier
	s_add_u32 s98, s40, s20
	s_addc_u32 s99, s41, s21
	s_add_u32 s100, s42, s20
	s_addc_u32 s101, s43, s21
	s_add_i32 s36, s54, s44
	s_mov_b32 m0, s36
	ds_read_b128 v[178:181], v196 offset:16384
	ds_read_b128 v[182:185], v196 offset:17408
	ds_read_b128 v[186:189], v196 offset:18432
	ds_read_b128 v[198:201], v196 offset:19456
	ds_read_b128 v[202:205], v196 offset:20480
	ds_read_b128 v[210:213], v196 offset:21504
	ds_read_b128 v[214:217], v196 offset:22528
	ds_read_b128 v[218:221], v196 offset:23552
	global_load_lds_dwordx4 v154, s[40:41]
	s_add_i32 m0, s36, 0x2000
	s_add_u32 s36, s40, 0xb0000
	s_addc_u32 s37, s41, 0
	s_add_i32 s63, s55, s44
	global_load_lds_dwordx4 v158, s[40:41]
	s_mov_b32 m0, s63
	s_nop 0
	global_load_lds_dwordx4 v154, s[36:37]
	s_add_i32 m0, s63, 0x2000
	s_nop 0
	global_load_lds_dwordx4 v158, s[36:37]
	s_mov_b32 m0, s45
	s_nop 0
	global_load_lds_dwordx4 v152, s[42:43]
	s_mov_b32 m0, s46
	s_nop 0
	global_load_lds_dwordx4 v156, s[42:43]
	s_waitcnt vmcnt(8)
	s_waitcnt lgkmcnt(0)
	s_barrier
	s_setprio 1
	s_waitcnt lgkmcnt(0)
	v_mfma_f32_16x16x32_bf16 v[60:63], v[128:131], v[178:181], v[60:63]
	v_mfma_f32_16x16x32_bf16 v[56:59], v[136:139], v[178:181], v[56:59]
	v_mfma_f32_16x16x32_bf16 v[44:47], v[128:131], v[186:189], v[44:47]
	v_mfma_f32_16x16x32_bf16 v[40:43], v[136:139], v[186:189], v[40:43]
	v_mfma_f32_16x16x32_bf16 v[28:31], v[128:131], v[202:205], v[28:31]
	v_mfma_f32_16x16x32_bf16 v[24:27], v[136:139], v[202:205], v[24:27]
	v_mfma_f32_16x16x32_bf16 v[12:15], v[128:131], v[214:217], v[12:15]
	v_mfma_f32_16x16x32_bf16 v[8:11], v[136:139], v[214:217], v[8:11]
	v_mfma_f32_16x16x32_bf16 v[60:63], v[132:135], v[182:185], v[60:63]
	v_mfma_f32_16x16x32_bf16 v[56:59], v[140:143], v[182:185], v[56:59]
	v_mfma_f32_16x16x32_bf16 v[44:47], v[132:135], v[198:201], v[44:47]
	v_mfma_f32_16x16x32_bf16 v[40:43], v[140:143], v[198:201], v[40:43]
	v_mfma_f32_16x16x32_bf16 v[28:31], v[132:135], v[210:213], v[28:31]
	v_mfma_f32_16x16x32_bf16 v[24:27], v[140:143], v[210:213], v[24:27]
	v_mfma_f32_16x16x32_bf16 v[12:15], v[132:135], v[218:221], v[12:15]
	v_mfma_f32_16x16x32_bf16 v[8:11], v[140:143], v[218:221], v[8:11]
	v_mfma_f32_16x16x32_bf16 v[52:55], v[144:147], v[178:181], v[52:55]
	v_mfma_f32_16x16x32_bf16 v[48:51], v[168:171], v[178:181], v[48:51]
	v_mfma_f32_16x16x32_bf16 v[36:39], v[144:147], v[186:189], v[36:39]
	v_mfma_f32_16x16x32_bf16 v[32:35], v[168:171], v[186:189], v[32:35]
	v_mfma_f32_16x16x32_bf16 v[20:23], v[144:147], v[202:205], v[20:23]
	v_mfma_f32_16x16x32_bf16 v[16:19], v[168:171], v[202:205], v[16:19]
	v_mfma_f32_16x16x32_bf16 v[4:7], v[144:147], v[214:217], v[4:7]
	v_mfma_f32_16x16x32_bf16 v[0:3], v[168:171], v[214:217], v[0:3]
	v_mfma_f32_16x16x32_bf16 v[52:55], v[148:151], v[182:185], v[52:55]
	v_mfma_f32_16x16x32_bf16 v[48:51], v[174:177], v[182:185], v[48:51]
	v_mfma_f32_16x16x32_bf16 v[36:39], v[148:151], v[198:201], v[36:39]
	v_mfma_f32_16x16x32_bf16 v[32:35], v[174:177], v[198:201], v[32:35]
	v_mfma_f32_16x16x32_bf16 v[20:23], v[148:151], v[210:213], v[20:23]
	v_mfma_f32_16x16x32_bf16 v[16:19], v[174:177], v[210:213], v[16:19]
	v_mfma_f32_16x16x32_bf16 v[4:7], v[148:151], v[218:221], v[4:7]
	v_mfma_f32_16x16x32_bf16 v[0:3], v[174:177], v[218:221], v[0:3]
	s_setprio 0
	s_barrier
	s_add_i32 s63, 0, 0x18000
	s_add_i32 s64, 0, 0x1c000
	v_add_u32_e32 v140, s63, v192
	v_add_u32_e32 v174, s64, v192
	ds_read_b128 v[128:131], v140
	ds_read_b128 v[132:135], v140 offset:1024
	ds_read_b128 v[136:139], v140 offset:2048
	ds_read_b128 v[140:143], v140 offset:3072
	ds_read_b128 v[144:147], v174
	ds_read_b128 v[148:151], v174 offset:1024
	ds_read_b128 v[168:171], v174 offset:2048
	ds_read_b128 v[174:177], v174 offset:3072
	s_add_u32 s36, s42, 0xb0000
	s_addc_u32 s37, s43, 0
	s_mov_b32 m0, s47
	ds_read_b128 v[178:181], v196 offset:32768
	ds_read_b128 v[182:185], v196 offset:33792
	ds_read_b128 v[186:189], v196 offset:34816
	ds_read_b128 v[198:201], v196 offset:35840
	ds_read_b128 v[202:205], v196 offset:36864
	ds_read_b128 v[210:213], v196 offset:37888
	ds_read_b128 v[214:217], v196 offset:38912
	ds_read_b128 v[218:221], v196 offset:39936
	global_load_lds_dwordx4 v152, s[36:37]
	s_mov_b32 m0, s48
	s_nop 0
	global_load_lds_dwordx4 v156, s[36:37]
	s_waitcnt vmcnt(8)
	s_waitcnt lgkmcnt(0)
	s_barrier
	s_setprio 1
	s_waitcnt lgkmcnt(0)
	v_mfma_f32_16x16x32_bf16 v[124:127], v[128:131], v[178:181], v[124:127]
	v_mfma_f32_16x16x32_bf16 v[120:123], v[136:139], v[178:181], v[120:123]
	v_mfma_f32_16x16x32_bf16 v[108:111], v[128:131], v[186:189], v[108:111]
	v_mfma_f32_16x16x32_bf16 v[104:107], v[136:139], v[186:189], v[104:107]
	v_mfma_f32_16x16x32_bf16 v[92:95], v[128:131], v[202:205], v[92:95]
	v_mfma_f32_16x16x32_bf16 v[88:91], v[136:139], v[202:205], v[88:91]
	v_mfma_f32_16x16x32_bf16 v[76:79], v[128:131], v[214:217], v[76:79]
	v_mfma_f32_16x16x32_bf16 v[72:75], v[136:139], v[214:217], v[72:75]
	v_mfma_f32_16x16x32_bf16 v[124:127], v[132:135], v[182:185], v[124:127]
	v_mfma_f32_16x16x32_bf16 v[120:123], v[140:143], v[182:185], v[120:123]
	v_mfma_f32_16x16x32_bf16 v[108:111], v[132:135], v[198:201], v[108:111]
	v_mfma_f32_16x16x32_bf16 v[104:107], v[140:143], v[198:201], v[104:107]
	v_mfma_f32_16x16x32_bf16 v[92:95], v[132:135], v[210:213], v[92:95]
	v_mfma_f32_16x16x32_bf16 v[88:91], v[140:143], v[210:213], v[88:91]
	v_mfma_f32_16x16x32_bf16 v[76:79], v[132:135], v[218:221], v[76:79]
	v_mfma_f32_16x16x32_bf16 v[72:75], v[140:143], v[218:221], v[72:75]
	v_mfma_f32_16x16x32_bf16 v[116:119], v[144:147], v[178:181], v[116:119]
	v_mfma_f32_16x16x32_bf16 v[112:115], v[168:171], v[178:181], v[112:115]
	v_mfma_f32_16x16x32_bf16 v[100:103], v[144:147], v[186:189], v[100:103]
	v_mfma_f32_16x16x32_bf16 v[96:99], v[168:171], v[186:189], v[96:99]
	v_mfma_f32_16x16x32_bf16 v[84:87], v[144:147], v[202:205], v[84:87]
	v_mfma_f32_16x16x32_bf16 v[80:83], v[168:171], v[202:205], v[80:83]
	v_mfma_f32_16x16x32_bf16 v[68:71], v[144:147], v[214:217], v[68:71]
	v_mfma_f32_16x16x32_bf16 v[64:67], v[168:171], v[214:217], v[64:67]
	v_mfma_f32_16x16x32_bf16 v[116:119], v[148:151], v[182:185], v[116:119]
	v_mfma_f32_16x16x32_bf16 v[112:115], v[174:177], v[182:185], v[112:115]
	v_mfma_f32_16x16x32_bf16 v[100:103], v[148:151], v[198:201], v[100:103]
	v_mfma_f32_16x16x32_bf16 v[96:99], v[174:177], v[198:201], v[96:99]
	v_mfma_f32_16x16x32_bf16 v[84:87], v[148:151], v[210:213], v[84:87]
	v_mfma_f32_16x16x32_bf16 v[80:83], v[174:177], v[210:213], v[80:83]
	v_mfma_f32_16x16x32_bf16 v[68:71], v[148:151], v[218:221], v[68:71]
	v_mfma_f32_16x16x32_bf16 v[64:67], v[174:177], v[218:221], v[64:67]
	s_setprio 0
	s_barrier
	s_add_i32 s36, s63, s44
	s_mov_b32 m0, s36
	ds_read_b128 v[178:181], v196 offset:49152
	ds_read_b128 v[182:185], v196 offset:50176
	ds_read_b128 v[186:189], v196 offset:51200
	ds_read_b128 v[198:201], v196 offset:52224
	ds_read_b128 v[202:205], v196 offset:53248
	ds_read_b128 v[210:213], v196 offset:54272
	ds_read_b128 v[214:217], v196 offset:55296
	ds_read_b128 v[218:221], v196 offset:56320
	global_load_lds_dwordx4 v154, s[98:99]
	s_add_i32 m0, s36, 0x2000
	s_add_u32 s36, s40, 0xb0080
	s_addc_u32 s37, s41, 0
	s_add_i32 s40, s64, s44
	global_load_lds_dwordx4 v158, s[98:99]
	s_mov_b32 m0, s40
	s_nop 0
	global_load_lds_dwordx4 v154, s[36:37]
	s_add_i32 m0, s40, 0x2000
	s_nop 0
	global_load_lds_dwordx4 v158, s[36:37]
	s_mov_b32 m0, s50
	s_nop 0
	global_load_lds_dwordx4 v152, s[100:101]
	s_mov_b32 m0, s51
	s_nop 0
	global_load_lds_dwordx4 v156, s[100:101]
	s_waitcnt vmcnt(8)
	s_waitcnt lgkmcnt(0)
	s_barrier
	s_setprio 1
	s_waitcnt lgkmcnt(0)
	v_mfma_f32_16x16x32_bf16 v[60:63], v[128:131], v[178:181], v[60:63]
	v_mfma_f32_16x16x32_bf16 v[56:59], v[136:139], v[178:181], v[56:59]
	v_mfma_f32_16x16x32_bf16 v[44:47], v[128:131], v[186:189], v[44:47]
	v_mfma_f32_16x16x32_bf16 v[40:43], v[136:139], v[186:189], v[40:43]
	v_mfma_f32_16x16x32_bf16 v[28:31], v[128:131], v[202:205], v[28:31]
	v_mfma_f32_16x16x32_bf16 v[24:27], v[136:139], v[202:205], v[24:27]
	v_mfma_f32_16x16x32_bf16 v[12:15], v[128:131], v[214:217], v[12:15]
	v_mfma_f32_16x16x32_bf16 v[8:11], v[136:139], v[214:217], v[8:11]
	v_mfma_f32_16x16x32_bf16 v[60:63], v[132:135], v[182:185], v[60:63]
	v_mfma_f32_16x16x32_bf16 v[56:59], v[140:143], v[182:185], v[56:59]
	v_mfma_f32_16x16x32_bf16 v[44:47], v[132:135], v[198:201], v[44:47]
	v_mfma_f32_16x16x32_bf16 v[40:43], v[140:143], v[198:201], v[40:43]
	v_mfma_f32_16x16x32_bf16 v[28:31], v[132:135], v[210:213], v[28:31]
	v_mfma_f32_16x16x32_bf16 v[24:27], v[140:143], v[210:213], v[24:27]
	v_mfma_f32_16x16x32_bf16 v[12:15], v[132:135], v[218:221], v[12:15]
	v_mfma_f32_16x16x32_bf16 v[8:11], v[140:143], v[218:221], v[8:11]
	v_mfma_f32_16x16x32_bf16 v[52:55], v[144:147], v[178:181], v[52:55]
	v_mfma_f32_16x16x32_bf16 v[48:51], v[168:171], v[178:181], v[48:51]
	v_mfma_f32_16x16x32_bf16 v[36:39], v[144:147], v[186:189], v[36:39]
	v_mfma_f32_16x16x32_bf16 v[32:35], v[168:171], v[186:189], v[32:35]
	v_mfma_f32_16x16x32_bf16 v[20:23], v[144:147], v[202:205], v[20:23]
	v_mfma_f32_16x16x32_bf16 v[16:19], v[168:171], v[202:205], v[16:19]
	v_mfma_f32_16x16x32_bf16 v[4:7], v[144:147], v[214:217], v[4:7]
	v_mfma_f32_16x16x32_bf16 v[0:3], v[168:171], v[214:217], v[0:3]
	v_mfma_f32_16x16x32_bf16 v[52:55], v[148:151], v[182:185], v[52:55]
	v_mfma_f32_16x16x32_bf16 v[48:51], v[174:177], v[182:185], v[48:51]
	v_mfma_f32_16x16x32_bf16 v[36:39], v[148:151], v[198:201], v[36:39]
	v_mfma_f32_16x16x32_bf16 v[32:35], v[174:177], v[198:201], v[32:35]
	v_mfma_f32_16x16x32_bf16 v[20:23], v[148:151], v[210:213], v[20:23]
	v_mfma_f32_16x16x32_bf16 v[16:19], v[174:177], v[210:213], v[16:19]
	v_mfma_f32_16x16x32_bf16 v[4:7], v[148:151], v[218:221], v[4:7]
	v_mfma_f32_16x16x32_bf16 v[0:3], v[174:177], v[218:221], v[0:3]
	s_setprio 0
	s_barrier
	s_add_i32 s62, s62, 2
	s_add_u32 s60, s60, 0x100
	s_addc_u32 s61, s61, 0
	s_cmp_gt_u32 s62, 41
	s_mov_b64 s[36:37], s[38:39]
	s_cbranch_scc0 .LBB0_741
	s_and_b64 vcc, exec, s[22:23]
	s_cbranch_vccz .LBB0_744
	s_barrier

.LBB0_836:
	ds_read_b128 v[88:91], v235
	ds_read_b128 v[92:95], v235 offset:1024
	ds_read_b128 v[104:107], v235 offset:2048
	ds_read_b128 v[108:111], v235 offset:3072
	ds_read_b128 v[136:139], v236
	ds_read_b128 v[140:143], v236 offset:1024
	ds_read_b128 v[148:151], v236 offset:2048
	ds_read_b128 v[152:155], v236 offset:3072
	s_add_u32 s42, s40, 0xfffc0080
	s_addc_u32 s43, s41, -1
	s_cmp_eq_u32 s63, 12
	s_cselect_b32 s45, s29, s43
	s_cselect_b32 s44, s37, s42
	s_cselect_b32 s43, s27, s62
	s_cselect_b32 s42, s39, s61
	s_add_i32 m0, s48, 0xc000
	ds_read_b128 v[160:163], v237
	ds_read_b128 v[164:167], v237 offset:1024
	ds_read_b128 v[168:171], v237 offset:2048
	ds_read_b128 v[172:175], v237 offset:3072
	ds_read_b128 v[176:179], v237 offset:4096
	ds_read_b128 v[180:183], v237 offset:5120
	ds_read_b128 v[184:187], v237 offset:6144
	ds_read_b128 v[188:191], v237 offset:7168
	global_load_lds_dwordx4 v200, s[40:41]
	s_add_i32 m0, s48, 0xe000
	s_nop 0
	global_load_lds_dwordx4 v202, s[40:41]
	s_waitcnt vmcnt(8)
	s_waitcnt lgkmcnt(0)
	s_barrier
	s_setprio 1
	s_waitcnt lgkmcnt(0)
	v_mfma_f32_16x16x32_bf16 v[124:127], v[88:91], v[160:163], v[124:127]
	v_mfma_f32_16x16x32_bf16 v[120:123], v[104:107], v[160:163], v[120:123]
	v_mfma_f32_16x16x32_bf16 v[156:159], v[88:91], v[168:171], v[156:159]
	v_mfma_f32_16x16x32_bf16 v[144:147], v[104:107], v[168:171], v[144:147]
	v_mfma_f32_16x16x32_bf16 v[100:103], v[88:91], v[176:179], v[100:103]
	v_mfma_f32_16x16x32_bf16 v[96:99], v[104:107], v[176:179], v[96:99]
	v_mfma_f32_16x16x32_bf16 v[76:79], v[88:91], v[184:187], v[76:79]
	v_mfma_f32_16x16x32_bf16 v[72:75], v[104:107], v[184:187], v[72:75]
	v_mfma_f32_16x16x32_bf16 v[124:127], v[92:95], v[164:167], v[124:127]
	v_mfma_f32_16x16x32_bf16 v[120:123], v[108:111], v[164:167], v[120:123]
	v_mfma_f32_16x16x32_bf16 v[156:159], v[92:95], v[172:175], v[156:159]
	v_mfma_f32_16x16x32_bf16 v[144:147], v[108:111], v[172:175], v[144:147]
	v_mfma_f32_16x16x32_bf16 v[100:103], v[92:95], v[180:183], v[100:103]
	v_mfma_f32_16x16x32_bf16 v[96:99], v[108:111], v[180:183], v[96:99]
	v_mfma_f32_16x16x32_bf16 v[76:79], v[92:95], v[188:191], v[76:79]
	v_mfma_f32_16x16x32_bf16 v[72:75], v[108:111], v[188:191], v[72:75]
	v_mfma_f32_16x16x32_bf16 v[116:119], v[136:139], v[160:163], v[116:119]
	v_mfma_f32_16x16x32_bf16 v[112:115], v[148:151], v[160:163], v[112:115]
	v_mfma_f32_16x16x32_bf16 v[132:135], v[136:139], v[168:171], v[132:135]
	v_mfma_f32_16x16x32_bf16 v[128:131], v[148:151], v[168:171], v[128:131]
	v_mfma_f32_16x16x32_bf16 v[84:87], v[136:139], v[176:179], v[84:87]
	v_mfma_f32_16x16x32_bf16 v[80:83], v[148:151], v[176:179], v[80:83]
	v_mfma_f32_16x16x32_bf16 v[68:71], v[136:139], v[184:187], v[68:71]
	v_mfma_f32_16x16x32_bf16 v[64:67], v[148:151], v[184:187], v[64:67]
	v_mfma_f32_16x16x32_bf16 v[116:119], v[140:143], v[164:167], v[116:119]
	v_mfma_f32_16x16x32_bf16 v[112:115], v[152:155], v[164:167], v[112:115]
	v_mfma_f32_16x16x32_bf16 v[132:135], v[140:143], v[172:175], v[132:135]
	v_mfma_f32_16x16x32_bf16 v[128:131], v[152:155], v[172:175], v[128:131]
	v_mfma_f32_16x16x32_bf16 v[84:87], v[140:143], v[180:183], v[84:87]
	v_mfma_f32_16x16x32_bf16 v[80:83], v[152:155], v[180:183], v[80:83]
	v_mfma_f32_16x16x32_bf16 v[68:71], v[140:143], v[188:191], v[68:71]
	v_mfma_f32_16x16x32_bf16 v[64:67], v[152:155], v[188:191], v[64:67]
	s_setprio 0
	s_barrier
	s_add_u32 s98, s42, s22
	s_addc_u32 s99, s43, s23
	s_add_u32 s100, s44, s22
	s_addc_u32 s101, s45, s23
	s_add_i32 s64, s59, s47
	s_mov_b32 m0, s64
	ds_read_b128 v[160:163], v237 offset:16384
	ds_read_b128 v[164:167], v237 offset:17408
	ds_read_b128 v[168:171], v237 offset:18432
	ds_read_b128 v[172:175], v237 offset:19456
	ds_read_b128 v[176:179], v237 offset:20480
	ds_read_b128 v[180:183], v237 offset:21504
	ds_read_b128 v[184:187], v237 offset:22528
	ds_read_b128 v[188:191], v237 offset:23552
	global_load_lds_dwordx4 v194, s[42:43]
	s_add_i32 m0, s64, 0x2000
	s_add_u32 s64, s42, 0x40000
	s_addc_u32 s65, s43, 0
	s_add_i32 s66, s60, s47
	global_load_lds_dwordx4 v198, s[42:43]
	s_mov_b32 m0, s66
	s_nop 0
	global_load_lds_dwordx4 v194, s[64:65]
	s_add_i32 m0, s66, 0x2000
	s_nop 0
	global_load_lds_dwordx4 v198, s[64:65]
	s_mov_b32 m0, s48
	s_nop 0
	global_load_lds_dwordx4 v192, s[44:45]
	s_mov_b32 m0, s49
	s_nop 0
	global_load_lds_dwordx4 v196, s[44:45]
	s_waitcnt vmcnt(8)
	s_waitcnt lgkmcnt(0)
	s_barrier
	s_setprio 1
	s_waitcnt lgkmcnt(0)
	v_mfma_f32_16x16x32_bf16 v[60:63], v[88:91], v[160:163], v[60:63]
	v_mfma_f32_16x16x32_bf16 v[56:59], v[104:107], v[160:163], v[56:59]
	v_mfma_f32_16x16x32_bf16 v[44:47], v[88:91], v[168:171], v[44:47]
	v_mfma_f32_16x16x32_bf16 v[40:43], v[104:107], v[168:171], v[40:43]
	v_mfma_f32_16x16x32_bf16 v[28:31], v[88:91], v[176:179], v[28:31]
	v_mfma_f32_16x16x32_bf16 v[24:27], v[104:107], v[176:179], v[24:27]
	v_mfma_f32_16x16x32_bf16 v[12:15], v[88:91], v[184:187], v[12:15]
	v_mfma_f32_16x16x32_bf16 v[8:11], v[104:107], v[184:187], v[8:11]
	v_mfma_f32_16x16x32_bf16 v[60:63], v[92:95], v[164:167], v[60:63]
	v_mfma_f32_16x16x32_bf16 v[56:59], v[108:111], v[164:167], v[56:59]
	v_mfma_f32_16x16x32_bf16 v[44:47], v[92:95], v[172:175], v[44:47]
	v_mfma_f32_16x16x32_bf16 v[40:43], v[108:111], v[172:175], v[40:43]
	v_mfma_f32_16x16x32_bf16 v[28:31], v[92:95], v[180:183], v[28:31]
	v_mfma_f32_16x16x32_bf16 v[24:27], v[108:111], v[180:183], v[24:27]
	v_mfma_f32_16x16x32_bf16 v[12:15], v[92:95], v[188:191], v[12:15]
	v_mfma_f32_16x16x32_bf16 v[8:11], v[108:111], v[188:191], v[8:11]
	v_mfma_f32_16x16x32_bf16 v[52:55], v[136:139], v[160:163], v[52:55]
	v_mfma_f32_16x16x32_bf16 v[48:51], v[148:151], v[160:163], v[48:51]
	v_mfma_f32_16x16x32_bf16 v[36:39], v[136:139], v[168:171], v[36:39]
	v_mfma_f32_16x16x32_bf16 v[32:35], v[148:151], v[168:171], v[32:35]
	v_mfma_f32_16x16x32_bf16 v[20:23], v[136:139], v[176:179], v[20:23]
	v_mfma_f32_16x16x32_bf16 v[16:19], v[148:151], v[176:179], v[16:19]
	v_mfma_f32_16x16x32_bf16 v[4:7], v[136:139], v[184:187], v[4:7]
	v_mfma_f32_16x16x32_bf16 v[0:3], v[148:151], v[184:187], v[0:3]
	v_mfma_f32_16x16x32_bf16 v[52:55], v[140:143], v[164:167], v[52:55]
	v_mfma_f32_16x16x32_bf16 v[48:51], v[152:155], v[164:167], v[48:51]
	v_mfma_f32_16x16x32_bf16 v[36:39], v[140:143], v[172:175], v[36:39]
	v_mfma_f32_16x16x32_bf16 v[32:35], v[152:155], v[172:175], v[32:35]
	v_mfma_f32_16x16x32_bf16 v[20:23], v[140:143], v[180:183], v[20:23]
	v_mfma_f32_16x16x32_bf16 v[16:19], v[152:155], v[180:183], v[16:19]
	v_mfma_f32_16x16x32_bf16 v[4:7], v[140:143], v[188:191], v[4:7]
	v_mfma_f32_16x16x32_bf16 v[0:3], v[152:155], v[188:191], v[0:3]
	s_setprio 0
	s_barrier
	s_add_i32 s64, 0, 0x18000
	s_add_i32 s65, 0, 0x1c000
	v_add_u32_e32 v108, s64, v233
	v_add_u32_e32 v152, s65, v233
	ds_read_b128 v[88:91], v108
	ds_read_b128 v[92:95], v108 offset:1024
	ds_read_b128 v[104:107], v108 offset:2048
	ds_read_b128 v[108:111], v108 offset:3072
	ds_read_b128 v[136:139], v152
	ds_read_b128 v[140:143], v152 offset:1024
	ds_read_b128 v[148:151], v152 offset:2048
	ds_read_b128 v[152:155], v152 offset:3072
	s_add_u32 s44, s44, 0x40000
	s_addc_u32 s45, s45, 0
	s_mov_b32 m0, s50
	ds_read_b128 v[160:163], v237 offset:32768
	ds_read_b128 v[164:167], v237 offset:33792
	ds_read_b128 v[168:171], v237 offset:34816
	ds_read_b128 v[172:175], v237 offset:35840
	ds_read_b128 v[176:179], v237 offset:36864
	ds_read_b128 v[180:183], v237 offset:37888
	ds_read_b128 v[184:187], v237 offset:38912
	ds_read_b128 v[188:191], v237 offset:39936
	global_load_lds_dwordx4 v192, s[44:45]
	s_mov_b32 m0, s51
	s_nop 0
	global_load_lds_dwordx4 v196, s[44:45]
	s_waitcnt vmcnt(8)
	s_waitcnt lgkmcnt(0)
	s_barrier
	s_setprio 1
	s_waitcnt lgkmcnt(0)
	v_mfma_f32_16x16x32_bf16 v[124:127], v[88:91], v[160:163], v[124:127]
	v_mfma_f32_16x16x32_bf16 v[120:123], v[104:107], v[160:163], v[120:123]
	v_mfma_f32_16x16x32_bf16 v[156:159], v[88:91], v[168:171], v[156:159]
	v_mfma_f32_16x16x32_bf16 v[144:147], v[104:107], v[168:171], v[144:147]
	v_mfma_f32_16x16x32_bf16 v[100:103], v[88:91], v[176:179], v[100:103]
	v_mfma_f32_16x16x32_bf16 v[96:99], v[104:107], v[176:179], v[96:99]
	v_mfma_f32_16x16x32_bf16 v[76:79], v[88:91], v[184:187], v[76:79]
	v_mfma_f32_16x16x32_bf16 v[72:75], v[104:107], v[184:187], v[72:75]
	v_mfma_f32_16x16x32_bf16 v[124:127], v[92:95], v[164:167], v[124:127]
	v_mfma_f32_16x16x32_bf16 v[120:123], v[108:111], v[164:167], v[120:123]
	v_mfma_f32_16x16x32_bf16 v[156:159], v[92:95], v[172:175], v[156:159]
	v_mfma_f32_16x16x32_bf16 v[144:147], v[108:111], v[172:175], v[144:147]
	v_mfma_f32_16x16x32_bf16 v[100:103], v[92:95], v[180:183], v[100:103]
	v_mfma_f32_16x16x32_bf16 v[96:99], v[108:111], v[180:183], v[96:99]
	v_mfma_f32_16x16x32_bf16 v[76:79], v[92:95], v[188:191], v[76:79]
	v_mfma_f32_16x16x32_bf16 v[72:75], v[108:111], v[188:191], v[72:75]
	v_mfma_f32_16x16x32_bf16 v[116:119], v[136:139], v[160:163], v[116:119]
	v_mfma_f32_16x16x32_bf16 v[112:115], v[148:151], v[160:163], v[112:115]
	v_mfma_f32_16x16x32_bf16 v[132:135], v[136:139], v[168:171], v[132:135]
	v_mfma_f32_16x16x32_bf16 v[128:131], v[148:151], v[168:171], v[128:131]
	v_mfma_f32_16x16x32_bf16 v[84:87], v[136:139], v[176:179], v[84:87]
	v_mfma_f32_16x16x32_bf16 v[80:83], v[148:151], v[176:179], v[80:83]
	v_mfma_f32_16x16x32_bf16 v[68:71], v[136:139], v[184:187], v[68:71]
	v_mfma_f32_16x16x32_bf16 v[64:67], v[148:151], v[184:187], v[64:67]
	v_mfma_f32_16x16x32_bf16 v[116:119], v[140:143], v[164:167], v[116:119]
	v_mfma_f32_16x16x32_bf16 v[112:115], v[152:155], v[164:167], v[112:115]
	v_mfma_f32_16x16x32_bf16 v[132:135], v[140:143], v[172:175], v[132:135]
	v_mfma_f32_16x16x32_bf16 v[128:131], v[152:155], v[172:175], v[128:131]
	v_mfma_f32_16x16x32_bf16 v[84:87], v[140:143], v[180:183], v[84:87]
	v_mfma_f32_16x16x32_bf16 v[80:83], v[152:155], v[180:183], v[80:83]
	v_mfma_f32_16x16x32_bf16 v[68:71], v[140:143], v[188:191], v[68:71]
	v_mfma_f32_16x16x32_bf16 v[64:67], v[152:155], v[188:191], v[64:67]
	s_setprio 0
	s_barrier
	s_add_i32 s44, s64, s47
	s_mov_b32 m0, s44
	ds_read_b128 v[160:163], v237 offset:49152
	ds_read_b128 v[164:167], v237 offset:50176
	ds_read_b128 v[168:171], v237 offset:51200
	ds_read_b128 v[172:175], v237 offset:52224
	ds_read_b128 v[176:179], v237 offset:53248
	ds_read_b128 v[180:183], v237 offset:54272
	ds_read_b128 v[184:187], v237 offset:55296
	ds_read_b128 v[188:191], v237 offset:56320
	global_load_lds_dwordx4 v194, s[98:99]
	s_add_i32 m0, s44, 0x2000
	s_add_u32 s42, s42, 0x40080
	s_addc_u32 s43, s43, 0
	s_add_i32 s44, s65, s47
	global_load_lds_dwordx4 v198, s[98:99]
	s_mov_b32 m0, s44
	s_nop 0
	global_load_lds_dwordx4 v194, s[42:43]
	s_add_i32 m0, s44, 0x2000
	s_nop 0
	global_load_lds_dwordx4 v198, s[42:43]
	s_mov_b32 m0, s55
	s_nop 0
	global_load_lds_dwordx4 v192, s[100:101]
	s_mov_b32 m0, s56
	s_nop 0
	global_load_lds_dwordx4 v196, s[100:101]
	s_waitcnt vmcnt(8)
	s_waitcnt lgkmcnt(0)
	s_barrier
	s_setprio 1
	s_waitcnt lgkmcnt(0)
	v_mfma_f32_16x16x32_bf16 v[60:63], v[88:91], v[160:163], v[60:63]
	v_mfma_f32_16x16x32_bf16 v[56:59], v[104:107], v[160:163], v[56:59]
	v_mfma_f32_16x16x32_bf16 v[44:47], v[88:91], v[168:171], v[44:47]
	v_mfma_f32_16x16x32_bf16 v[40:43], v[104:107], v[168:171], v[40:43]
	v_mfma_f32_16x16x32_bf16 v[28:31], v[88:91], v[176:179], v[28:31]
	v_mfma_f32_16x16x32_bf16 v[24:27], v[104:107], v[176:179], v[24:27]
	v_mfma_f32_16x16x32_bf16 v[12:15], v[88:91], v[184:187], v[12:15]
	v_mfma_f32_16x16x32_bf16 v[8:11], v[104:107], v[184:187], v[8:11]
	v_mfma_f32_16x16x32_bf16 v[60:63], v[92:95], v[164:167], v[60:63]
	v_mfma_f32_16x16x32_bf16 v[56:59], v[108:111], v[164:167], v[56:59]
	v_mfma_f32_16x16x32_bf16 v[44:47], v[92:95], v[172:175], v[44:47]
	v_mfma_f32_16x16x32_bf16 v[40:43], v[108:111], v[172:175], v[40:43]
	v_mfma_f32_16x16x32_bf16 v[28:31], v[92:95], v[180:183], v[28:31]
	v_mfma_f32_16x16x32_bf16 v[24:27], v[108:111], v[180:183], v[24:27]
	v_mfma_f32_16x16x32_bf16 v[12:15], v[92:95], v[188:191], v[12:15]
	v_mfma_f32_16x16x32_bf16 v[8:11], v[108:111], v[188:191], v[8:11]
	v_mfma_f32_16x16x32_bf16 v[52:55], v[136:139], v[160:163], v[52:55]
	v_mfma_f32_16x16x32_bf16 v[48:51], v[148:151], v[160:163], v[48:51]
	v_mfma_f32_16x16x32_bf16 v[36:39], v[136:139], v[168:171], v[36:39]
	v_mfma_f32_16x16x32_bf16 v[32:35], v[148:151], v[168:171], v[32:35]
	v_mfma_f32_16x16x32_bf16 v[20:23], v[136:139], v[176:179], v[20:23]
	v_mfma_f32_16x16x32_bf16 v[16:19], v[148:151], v[176:179], v[16:19]
	v_mfma_f32_16x16x32_bf16 v[4:7], v[136:139], v[184:187], v[4:7]
	v_mfma_f32_16x16x32_bf16 v[0:3], v[148:151], v[184:187], v[0:3]
	v_mfma_f32_16x16x32_bf16 v[52:55], v[140:143], v[164:167], v[52:55]
	v_mfma_f32_16x16x32_bf16 v[48:51], v[152:155], v[164:167], v[48:51]
	v_mfma_f32_16x16x32_bf16 v[36:39], v[140:143], v[172:175], v[36:39]
	v_mfma_f32_16x16x32_bf16 v[32:35], v[152:155], v[172:175], v[32:35]
	v_mfma_f32_16x16x32_bf16 v[20:23], v[140:143], v[180:183], v[20:23]
	v_mfma_f32_16x16x32_bf16 v[16:19], v[152:155], v[180:183], v[16:19]
	v_mfma_f32_16x16x32_bf16 v[4:7], v[140:143], v[188:191], v[4:7]
	v_mfma_f32_16x16x32_bf16 v[0:3], v[152:155], v[188:191], v[0:3]
	s_setprio 0
	s_barrier
	s_add_i32 s63, s63, 2
	s_add_u32 s40, s40, 0x100
	s_addc_u32 s41, s41, 0
	s_add_u32 s61, s61, 0x100
	s_addc_u32 s62, s62, 0
	s_cmp_gt_u32 s63, 13
	s_cbranch_scc0 .LBB0_836
	s_and_b64 vcc, exec, s[24:25]
	s_cbranch_vccz .LBB0_839
	s_barrier
